# v6: hand-written streamlined epilogues for PROJN gate/latent tiles, W1, PROJT (loads hoisted, no per-call switch), on top of v3
# speedup vs baseline: 1.0359x; 1.0242x over previous
.LBB0_435:
	s_cmp_eq_u32 s31, 2
	s_cbranch_scc1 .Lepi_ya
	s_cmp_eq_u32 s31, 6
	s_cbranch_scc1 .Lepi_yb
	s_cmp_eq_u32 s31, 7
	s_cbranch_scc1 .Lepi_wout
	s_cmp_eq_u32 s31, 9
	s_cbranch_scc1 .Lepi_w2
	s_cmp_eq_u32 s31, 3
	s_cbranch_scc1 .Lepi_qup
	s_cmp_eq_u32 s31, 4
	s_cbranch_scc1 .Lepi_kup
	s_cmp_eq_u32 s31, 5
	s_cbranch_scc1 .Lepi_vupt
	s_cmp_lg_u32 s31, 0
	s_cbranch_scc1 .Lepi_noprojn
	s_add_i32 s46, s8, -6
	s_cmp_lt_u32 s46, 8
	s_cbranch_scc1 .Lepi_projn_g
	s_cmp_ge_u32 s8, 14
	s_cbranch_scc1 .Lepi_projn_lat
.Lepi_noprojn:
	s_cmp_eq_u32 s31, 8
	s_cbranch_scc1 .Lepi_w1
	s_cmp_eq_u32 s31, 1
	s_cbranch_scc1 .Lepi_projt
	s_lshl_b32 s9, s9, 8
	s_add_i32 s9, s9, s60
	s_lshl_b32 s78, s8, 8
	v_or_b32_e32 v154, s9, v1
	s_ashr_i32 s41, s9, 11
	v_ashrrev_i32_e32 v155, 31, v154
	s_or_b32 s38, s78, s26
	s_mul_hi_i32 s48, s41, 0x6000
	s_mulk_i32 s41, 0x6000
	v_lshlrev_b64 v[158:159], 10, v[154:155]
	v_lshlrev_b64 v[170:171], 13, v[154:155]
	v_lshlrev_b64 v[156:157], 7, v[154:155]
	v_cmp_gt_i32_e64 s[46:47], s33, v154
	v_or_b32_e32 v152, s38, v176
	s_cmp_lt_i32 s31, 5
	s_mov_b64 s[74:75], -1
	s_cbranch_scc1 .LBB0_454
	s_cmp_lt_i32 s31, 7
	s_cbranch_scc1 .LBB0_448
	s_cmp_lt_i32 s31, 8
	s_cbranch_scc1 .LBB0_445
	s_cmp_lt_i32 s31, 9
	s_cbranch_scc1 .LBB0_442
	s_cmp_eq_u32 s31, 9
	s_cbranch_scc0 .LBB0_441
	s_add_u32 s68, s36, s41
	v_ashrrev_i32_e32 v153, 31, v152
	s_addc_u32 s69, s37, s48
	v_lshlrev_b64 v[168:169], 2, v[152:153]
	v_lshl_add_u64 v[164:165], s[68:69], 0, v[168:169]
	v_lshlrev_b64 v[172:173], 2, v[158:159]
	v_add_co_u32_e32 v130, vcc, 0x5000, v164
	v_lshl_add_u64 v[134:135], s[94:95], 0, v[172:173]
	s_nop 0
	v_addc_co_u32_e32 v131, vcc, 0, v165, vcc
	v_lshl_add_u64 v[174:175], v[134:135], 0, v[168:169]
	s_mov_b64 s[68:69], 0x5000
	global_load_dwordx4 v[130:133], v[130:131], off
	s_nop 0
	global_load_dwordx4 v[134:137], v[174:175], off offset:16
	global_load_dwordx4 v[160:163], v[174:175], off
	v_lshl_add_u64 v[164:165], v[164:165], 0, s[68:69]
	global_load_dwordx4 v[164:167], v[164:165], off offset:16
	v_lshl_add_u64 v[172:173], s[54:55], 0, v[172:173]
	v_lshl_add_u64 v[168:169], v[172:173], 0, v[168:169]
	v_cndmask_b32_e64 v169, v169, v175, s[42:43]
	v_cndmask_b32_e64 v168, v168, v174, s[42:43]
	s_waitcnt vmcnt(0)
	v_pk_fma_f32 v[132:133], v[128:129], v[132:133], v[162:163]
	v_pk_fma_f32 v[130:131], v[126:127], v[130:131], v[160:161]
	v_pk_fma_f32 v[136:137], v[124:125], v[166:167], v[136:137]
	v_pk_fma_f32 v[134:135], v[122:123], v[164:165], v[134:135]
	global_store_dwordx4 v[168:169], v[130:133], off nt
	global_store_dwordx4 v[168:169], v[134:137], off offset:16 nt

.Lepi_projn_g:
	s_lshl_b32 s9, s9, 8
	s_add_i32 s9, s9, s60
	s_lshl_b32 s78, s8, 8
	s_or_b32 s78, s78, s26
	s_add_i32 s78, s78, 0xfffffa00
	v_readlane_b32 s68, v255, 32
	v_readlane_b32 s69, v255, 33
	s_lshl_b32 s41, s78, 2
	s_nop 1
	s_add_u32 s68, s68, s41
	s_addc_u32 s69, s69, 0
	v_lshlrev_b32_e32 v131, 2, v176
	global_load_dwordx4 v[132:135], v131, s[68:69] offset:0
	global_load_dwordx4 v[152:155], v131, s[68:69] offset:16
	global_load_dwordx4 v[156:159], v131, s[68:69] offset:512
	global_load_dwordx4 v[160:163], v131, s[68:69] offset:528
	s_cmp_lt_u32 s8, 10
	s_cselect_b32 s41, 0, 0x400
	s_mov_b32 s48, 0x3600000
	s_cselect_b32 s48, s48, 0x7600000
	s_sub_i32 s78, s78, s41
	s_lshl_b32 s78, s78, 1
	s_lshl_b32 s9, s9, 11
	s_add_i32 s9, s9, s78
	s_add_u32 s46, s36, s9
	s_addc_u32 s47, s37, 0
	s_add_u32 s46, s46, s48
	s_addc_u32 s47, s47, 0
	v_lshlrev_b32_e32 v130, 11, v1
	v_lshl_add_u32 v130, v176, 1, v130
	s_waitcnt vmcnt(0)
	v_add_f32_e32 v164, v126, v132
	v_add_f32_e32 v165, v127, v133
	v_add_f32_e32 v166, v128, v134
	v_add_f32_e32 v167, v129, v135
	v_add_f32_e32 v168, v122, v152
	v_add_f32_e32 v169, v123, v153
	v_add_f32_e32 v170, v124, v154
	v_add_f32_e32 v171, v125, v155
	v_mul_f32_e32 v164, 0xbfb8aa3b, v164
	v_mul_f32_e32 v165, 0xbfb8aa3b, v165
	v_mul_f32_e32 v166, 0xbfb8aa3b, v166
	v_mul_f32_e32 v167, 0xbfb8aa3b, v167
	v_mul_f32_e32 v168, 0xbfb8aa3b, v168
	v_mul_f32_e32 v169, 0xbfb8aa3b, v169
	v_mul_f32_e32 v170, 0xbfb8aa3b, v170
	v_mul_f32_e32 v171, 0xbfb8aa3b, v171
	v_exp_f32_e32 v164, v164
	v_exp_f32_e32 v165, v165
	v_exp_f32_e32 v166, v166
	v_exp_f32_e32 v167, v167
	v_exp_f32_e32 v168, v168
	v_exp_f32_e32 v169, v169
	v_exp_f32_e32 v170, v170
	v_exp_f32_e32 v171, v171
	v_add_f32_e32 v164, 1.0, v164
	v_add_f32_e32 v165, 1.0, v165
	v_add_f32_e32 v166, 1.0, v166
	v_add_f32_e32 v167, 1.0, v167
	v_add_f32_e32 v168, 1.0, v168
	v_add_f32_e32 v169, 1.0, v169
	v_add_f32_e32 v170, 1.0, v170
	v_add_f32_e32 v171, 1.0, v171
	v_rcp_f32_e32 v164, v164
	v_rcp_f32_e32 v165, v165
	v_rcp_f32_e32 v166, v166
	v_rcp_f32_e32 v167, v167
	v_rcp_f32_e32 v168, v168
	v_rcp_f32_e32 v169, v169
	v_rcp_f32_e32 v170, v170
	v_rcp_f32_e32 v171, v171
	v_cvt_pk_bf16_f32 v172, v164, v165
	v_cvt_pk_bf16_f32 v173, v166, v167
	v_cvt_pk_bf16_f32 v174, v168, v169
	v_cvt_pk_bf16_f32 v175, v170, v171
	global_store_dwordx4 v130, v[172:175], s[46:47] nt
	v_add_f32_e32 v180, v118, v156
	v_add_f32_e32 v181, v119, v157
	v_add_f32_e32 v182, v120, v158
	v_add_f32_e32 v183, v121, v159
	v_add_f32_e32 v184, v114, v160
	v_add_f32_e32 v185, v115, v161
	v_add_f32_e32 v186, v116, v162
	v_add_f32_e32 v187, v117, v163
	v_mul_f32_e32 v180, 0xbfb8aa3b, v180
	v_mul_f32_e32 v181, 0xbfb8aa3b, v181
	v_mul_f32_e32 v182, 0xbfb8aa3b, v182
	v_mul_f32_e32 v183, 0xbfb8aa3b, v183
	v_mul_f32_e32 v184, 0xbfb8aa3b, v184
	v_mul_f32_e32 v185, 0xbfb8aa3b, v185
	v_mul_f32_e32 v186, 0xbfb8aa3b, v186
	v_mul_f32_e32 v187, 0xbfb8aa3b, v187
	v_exp_f32_e32 v180, v180
	v_exp_f32_e32 v181, v181
	v_exp_f32_e32 v182, v182
	v_exp_f32_e32 v183, v183
	v_exp_f32_e32 v184, v184
	v_exp_f32_e32 v185, v185
	v_exp_f32_e32 v186, v186
	v_exp_f32_e32 v187, v187
	v_add_f32_e32 v180, 1.0, v180
	v_add_f32_e32 v181, 1.0, v181
	v_add_f32_e32 v182, 1.0, v182
	v_add_f32_e32 v183, 1.0, v183
	v_add_f32_e32 v184, 1.0, v184
	v_add_f32_e32 v185, 1.0, v185
	v_add_f32_e32 v186, 1.0, v186
	v_add_f32_e32 v187, 1.0, v187
	v_rcp_f32_e32 v180, v180
	v_rcp_f32_e32 v181, v181
	v_rcp_f32_e32 v182, v182
	v_rcp_f32_e32 v183, v183
	v_rcp_f32_e32 v184, v184
	v_rcp_f32_e32 v185, v185
	v_rcp_f32_e32 v186, v186
	v_rcp_f32_e32 v187, v187
	v_cvt_pk_bf16_f32 v188, v180, v181
	v_cvt_pk_bf16_f32 v189, v182, v183
	v_cvt_pk_bf16_f32 v190, v184, v185
	v_cvt_pk_bf16_f32 v191, v186, v187
	global_store_dwordx4 v130, v[188:191], s[46:47] offset:256 nt
	v_add_f32_e32 v164, v110, v132
	v_add_f32_e32 v165, v111, v133
	v_add_f32_e32 v166, v112, v134
	v_add_f32_e32 v167, v113, v135
	v_add_f32_e32 v168, v106, v152
	v_add_f32_e32 v169, v107, v153
	v_add_f32_e32 v170, v108, v154
	v_add_f32_e32 v171, v109, v155
	v_mul_f32_e32 v164, 0xbfb8aa3b, v164
	v_mul_f32_e32 v165, 0xbfb8aa3b, v165
	v_mul_f32_e32 v166, 0xbfb8aa3b, v166
	v_mul_f32_e32 v167, 0xbfb8aa3b, v167
	v_mul_f32_e32 v168, 0xbfb8aa3b, v168
	v_mul_f32_e32 v169, 0xbfb8aa3b, v169
	v_mul_f32_e32 v170, 0xbfb8aa3b, v170
	v_mul_f32_e32 v171, 0xbfb8aa3b, v171
	v_exp_f32_e32 v164, v164
	v_exp_f32_e32 v165, v165
	v_exp_f32_e32 v166, v166
	v_exp_f32_e32 v167, v167
	v_exp_f32_e32 v168, v168
	v_exp_f32_e32 v169, v169
	v_exp_f32_e32 v170, v170
	v_exp_f32_e32 v171, v171
	v_add_f32_e32 v164, 1.0, v164
	v_add_f32_e32 v165, 1.0, v165
	v_add_f32_e32 v166, 1.0, v166
	v_add_f32_e32 v167, 1.0, v167
	v_add_f32_e32 v168, 1.0, v168
	v_add_f32_e32 v169, 1.0, v169
	v_add_f32_e32 v170, 1.0, v170
	v_add_f32_e32 v171, 1.0, v171
	v_rcp_f32_e32 v164, v164
	v_rcp_f32_e32 v165, v165
	v_rcp_f32_e32 v166, v166
	v_rcp_f32_e32 v167, v167
	v_rcp_f32_e32 v168, v168
	v_rcp_f32_e32 v169, v169
	v_rcp_f32_e32 v170, v170
	v_rcp_f32_e32 v171, v171
	v_cvt_pk_bf16_f32 v172, v164, v165
	v_cvt_pk_bf16_f32 v173, v166, v167
	v_cvt_pk_bf16_f32 v174, v168, v169
	v_cvt_pk_bf16_f32 v175, v170, v171
	s_add_u32 s46, s46, 0x8000
	s_addc_u32 s47, s47, 0
	global_store_dwordx4 v130, v[172:175], s[46:47] nt
	v_add_f32_e32 v180, v102, v156
	v_add_f32_e32 v181, v103, v157
	v_add_f32_e32 v182, v104, v158
	v_add_f32_e32 v183, v105, v159
	v_add_f32_e32 v184, v98, v160
	v_add_f32_e32 v185, v99, v161
	v_add_f32_e32 v186, v100, v162
	v_add_f32_e32 v187, v101, v163
	v_mul_f32_e32 v180, 0xbfb8aa3b, v180
	v_mul_f32_e32 v181, 0xbfb8aa3b, v181
	v_mul_f32_e32 v182, 0xbfb8aa3b, v182
	v_mul_f32_e32 v183, 0xbfb8aa3b, v183
	v_mul_f32_e32 v184, 0xbfb8aa3b, v184
	v_mul_f32_e32 v185, 0xbfb8aa3b, v185
	v_mul_f32_e32 v186, 0xbfb8aa3b, v186
	v_mul_f32_e32 v187, 0xbfb8aa3b, v187
	v_exp_f32_e32 v180, v180
	v_exp_f32_e32 v181, v181
	v_exp_f32_e32 v182, v182
	v_exp_f32_e32 v183, v183
	v_exp_f32_e32 v184, v184
	v_exp_f32_e32 v185, v185
	v_exp_f32_e32 v186, v186
	v_exp_f32_e32 v187, v187
	v_add_f32_e32 v180, 1.0, v180
	v_add_f32_e32 v181, 1.0, v181
	v_add_f32_e32 v182, 1.0, v182
	v_add_f32_e32 v183, 1.0, v183
	v_add_f32_e32 v184, 1.0, v184
	v_add_f32_e32 v185, 1.0, v185
	v_add_f32_e32 v186, 1.0, v186
	v_add_f32_e32 v187, 1.0, v187
	v_rcp_f32_e32 v180, v180
	v_rcp_f32_e32 v181, v181
	v_rcp_f32_e32 v182, v182
	v_rcp_f32_e32 v183, v183
	v_rcp_f32_e32 v184, v184
	v_rcp_f32_e32 v185, v185
	v_rcp_f32_e32 v186, v186
	v_rcp_f32_e32 v187, v187
	v_cvt_pk_bf16_f32 v188, v180, v181
	v_cvt_pk_bf16_f32 v189, v182, v183
	v_cvt_pk_bf16_f32 v190, v184, v185
	v_cvt_pk_bf16_f32 v191, v186, v187
	global_store_dwordx4 v130, v[188:191], s[46:47] offset:256 nt
	v_add_f32_e32 v164, v94, v132
	v_add_f32_e32 v165, v95, v133
	v_add_f32_e32 v166, v96, v134
	v_add_f32_e32 v167, v97, v135
	v_add_f32_e32 v168, v90, v152
	v_add_f32_e32 v169, v91, v153
	v_add_f32_e32 v170, v92, v154
	v_add_f32_e32 v171, v93, v155
	v_mul_f32_e32 v164, 0xbfb8aa3b, v164
	v_mul_f32_e32 v165, 0xbfb8aa3b, v165
	v_mul_f32_e32 v166, 0xbfb8aa3b, v166
	v_mul_f32_e32 v167, 0xbfb8aa3b, v167
	v_mul_f32_e32 v168, 0xbfb8aa3b, v168
	v_mul_f32_e32 v169, 0xbfb8aa3b, v169
	v_mul_f32_e32 v170, 0xbfb8aa3b, v170
	v_mul_f32_e32 v171, 0xbfb8aa3b, v171
	v_exp_f32_e32 v164, v164
	v_exp_f32_e32 v165, v165
	v_exp_f32_e32 v166, v166
	v_exp_f32_e32 v167, v167
	v_exp_f32_e32 v168, v168
	v_exp_f32_e32 v169, v169
	v_exp_f32_e32 v170, v170
	v_exp_f32_e32 v171, v171
	v_add_f32_e32 v164, 1.0, v164
	v_add_f32_e32 v165, 1.0, v165
	v_add_f32_e32 v166, 1.0, v166
	v_add_f32_e32 v167, 1.0, v167
	v_add_f32_e32 v168, 1.0, v168
	v_add_f32_e32 v169, 1.0, v169
	v_add_f32_e32 v170, 1.0, v170
	v_add_f32_e32 v171, 1.0, v171
	v_rcp_f32_e32 v164, v164
	v_rcp_f32_e32 v165, v165
	v_rcp_f32_e32 v166, v166
	v_rcp_f32_e32 v167, v167
	v_rcp_f32_e32 v168, v168
	v_rcp_f32_e32 v169, v169
	v_rcp_f32_e32 v170, v170
	v_rcp_f32_e32 v171, v171
	v_cvt_pk_bf16_f32 v172, v164, v165
	v_cvt_pk_bf16_f32 v173, v166, v167
	v_cvt_pk_bf16_f32 v174, v168, v169
	v_cvt_pk_bf16_f32 v175, v170, v171
	s_add_u32 s46, s46, 0x8000
	s_addc_u32 s47, s47, 0
	global_store_dwordx4 v130, v[172:175], s[46:47] nt
	v_add_f32_e32 v180, v86, v156
	v_add_f32_e32 v181, v87, v157
	v_add_f32_e32 v182, v88, v158
	v_add_f32_e32 v183, v89, v159
	v_add_f32_e32 v184, v82, v160
	v_add_f32_e32 v185, v83, v161
	v_add_f32_e32 v186, v84, v162
	v_add_f32_e32 v187, v85, v163
	v_mul_f32_e32 v180, 0xbfb8aa3b, v180
	v_mul_f32_e32 v181, 0xbfb8aa3b, v181
	v_mul_f32_e32 v182, 0xbfb8aa3b, v182
	v_mul_f32_e32 v183, 0xbfb8aa3b, v183
	v_mul_f32_e32 v184, 0xbfb8aa3b, v184
	v_mul_f32_e32 v185, 0xbfb8aa3b, v185
	v_mul_f32_e32 v186, 0xbfb8aa3b, v186
	v_mul_f32_e32 v187, 0xbfb8aa3b, v187
	v_exp_f32_e32 v180, v180
	v_exp_f32_e32 v181, v181
	v_exp_f32_e32 v182, v182
	v_exp_f32_e32 v183, v183
	v_exp_f32_e32 v184, v184
	v_exp_f32_e32 v185, v185
	v_exp_f32_e32 v186, v186
	v_exp_f32_e32 v187, v187
	v_add_f32_e32 v180, 1.0, v180
	v_add_f32_e32 v181, 1.0, v181
	v_add_f32_e32 v182, 1.0, v182
	v_add_f32_e32 v183, 1.0, v183
	v_add_f32_e32 v184, 1.0, v184
	v_add_f32_e32 v185, 1.0, v185
	v_add_f32_e32 v186, 1.0, v186
	v_add_f32_e32 v187, 1.0, v187
	v_rcp_f32_e32 v180, v180
	v_rcp_f32_e32 v181, v181
	v_rcp_f32_e32 v182, v182
	v_rcp_f32_e32 v183, v183
	v_rcp_f32_e32 v184, v184
	v_rcp_f32_e32 v185, v185
	v_rcp_f32_e32 v186, v186
	v_rcp_f32_e32 v187, v187
	v_cvt_pk_bf16_f32 v188, v180, v181
	v_cvt_pk_bf16_f32 v189, v182, v183
	v_cvt_pk_bf16_f32 v190, v184, v185
	v_cvt_pk_bf16_f32 v191, v186, v187
	global_store_dwordx4 v130, v[188:191], s[46:47] offset:256 nt
	v_add_f32_e32 v164, v78, v132
	v_add_f32_e32 v165, v79, v133
	v_add_f32_e32 v166, v80, v134
	v_add_f32_e32 v167, v81, v135
	v_add_f32_e32 v168, v74, v152
	v_add_f32_e32 v169, v75, v153
	v_add_f32_e32 v170, v76, v154
	v_add_f32_e32 v171, v77, v155
	v_mul_f32_e32 v164, 0xbfb8aa3b, v164
	v_mul_f32_e32 v165, 0xbfb8aa3b, v165
	v_mul_f32_e32 v166, 0xbfb8aa3b, v166
	v_mul_f32_e32 v167, 0xbfb8aa3b, v167
	v_mul_f32_e32 v168, 0xbfb8aa3b, v168
	v_mul_f32_e32 v169, 0xbfb8aa3b, v169
	v_mul_f32_e32 v170, 0xbfb8aa3b, v170
	v_mul_f32_e32 v171, 0xbfb8aa3b, v171
	v_exp_f32_e32 v164, v164
	v_exp_f32_e32 v165, v165
	v_exp_f32_e32 v166, v166
	v_exp_f32_e32 v167, v167
	v_exp_f32_e32 v168, v168
	v_exp_f32_e32 v169, v169
	v_exp_f32_e32 v170, v170
	v_exp_f32_e32 v171, v171
	v_add_f32_e32 v164, 1.0, v164
	v_add_f32_e32 v165, 1.0, v165
	v_add_f32_e32 v166, 1.0, v166
	v_add_f32_e32 v167, 1.0, v167
	v_add_f32_e32 v168, 1.0, v168
	v_add_f32_e32 v169, 1.0, v169
	v_add_f32_e32 v170, 1.0, v170
	v_add_f32_e32 v171, 1.0, v171
	v_rcp_f32_e32 v164, v164
	v_rcp_f32_e32 v165, v165
	v_rcp_f32_e32 v166, v166
	v_rcp_f32_e32 v167, v167
	v_rcp_f32_e32 v168, v168
	v_rcp_f32_e32 v169, v169
	v_rcp_f32_e32 v170, v170
	v_rcp_f32_e32 v171, v171
	v_cvt_pk_bf16_f32 v172, v164, v165
	v_cvt_pk_bf16_f32 v173, v166, v167
	v_cvt_pk_bf16_f32 v174, v168, v169
	v_cvt_pk_bf16_f32 v175, v170, v171
	s_add_u32 s46, s46, 0x8000
	s_addc_u32 s47, s47, 0
	global_store_dwordx4 v130, v[172:175], s[46:47] nt
	v_add_f32_e32 v180, v70, v156
	v_add_f32_e32 v181, v71, v157
	v_add_f32_e32 v182, v72, v158
	v_add_f32_e32 v183, v73, v159
	v_add_f32_e32 v184, v66, v160
	v_add_f32_e32 v185, v67, v161
	v_add_f32_e32 v186, v68, v162
	v_add_f32_e32 v187, v69, v163
	v_mul_f32_e32 v180, 0xbfb8aa3b, v180
	v_mul_f32_e32 v181, 0xbfb8aa3b, v181
	v_mul_f32_e32 v182, 0xbfb8aa3b, v182
	v_mul_f32_e32 v183, 0xbfb8aa3b, v183
	v_mul_f32_e32 v184, 0xbfb8aa3b, v184
	v_mul_f32_e32 v185, 0xbfb8aa3b, v185
	v_mul_f32_e32 v186, 0xbfb8aa3b, v186
	v_mul_f32_e32 v187, 0xbfb8aa3b, v187
	v_exp_f32_e32 v180, v180
	v_exp_f32_e32 v181, v181
	v_exp_f32_e32 v182, v182
	v_exp_f32_e32 v183, v183
	v_exp_f32_e32 v184, v184
	v_exp_f32_e32 v185, v185
	v_exp_f32_e32 v186, v186
	v_exp_f32_e32 v187, v187
	v_add_f32_e32 v180, 1.0, v180
	v_add_f32_e32 v181, 1.0, v181
	v_add_f32_e32 v182, 1.0, v182
	v_add_f32_e32 v183, 1.0, v183
	v_add_f32_e32 v184, 1.0, v184
	v_add_f32_e32 v185, 1.0, v185
	v_add_f32_e32 v186, 1.0, v186
	v_add_f32_e32 v187, 1.0, v187
	v_rcp_f32_e32 v180, v180
	v_rcp_f32_e32 v181, v181
	v_rcp_f32_e32 v182, v182
	v_rcp_f32_e32 v183, v183
	v_rcp_f32_e32 v184, v184
	v_rcp_f32_e32 v185, v185
	v_rcp_f32_e32 v186, v186
	v_rcp_f32_e32 v187, v187
	v_cvt_pk_bf16_f32 v188, v180, v181
	v_cvt_pk_bf16_f32 v189, v182, v183
	v_cvt_pk_bf16_f32 v190, v184, v185
	v_cvt_pk_bf16_f32 v191, v186, v187
	global_store_dwordx4 v130, v[188:191], s[46:47] offset:256 nt
	v_add_f32_e32 v164, v62, v132
	v_add_f32_e32 v165, v63, v133
	v_add_f32_e32 v166, v64, v134
	v_add_f32_e32 v167, v65, v135
	v_add_f32_e32 v168, v58, v152
	v_add_f32_e32 v169, v59, v153
	v_add_f32_e32 v170, v60, v154
	v_add_f32_e32 v171, v61, v155
	v_mul_f32_e32 v164, 0xbfb8aa3b, v164
	v_mul_f32_e32 v165, 0xbfb8aa3b, v165
	v_mul_f32_e32 v166, 0xbfb8aa3b, v166
	v_mul_f32_e32 v167, 0xbfb8aa3b, v167
	v_mul_f32_e32 v168, 0xbfb8aa3b, v168
	v_mul_f32_e32 v169, 0xbfb8aa3b, v169
	v_mul_f32_e32 v170, 0xbfb8aa3b, v170
	v_mul_f32_e32 v171, 0xbfb8aa3b, v171
	v_exp_f32_e32 v164, v164
	v_exp_f32_e32 v165, v165
	v_exp_f32_e32 v166, v166
	v_exp_f32_e32 v167, v167
	v_exp_f32_e32 v168, v168
	v_exp_f32_e32 v169, v169
	v_exp_f32_e32 v170, v170
	v_exp_f32_e32 v171, v171
	v_add_f32_e32 v164, 1.0, v164
	v_add_f32_e32 v165, 1.0, v165
	v_add_f32_e32 v166, 1.0, v166
	v_add_f32_e32 v167, 1.0, v167
	v_add_f32_e32 v168, 1.0, v168
	v_add_f32_e32 v169, 1.0, v169
	v_add_f32_e32 v170, 1.0, v170
	v_add_f32_e32 v171, 1.0, v171
	v_rcp_f32_e32 v164, v164
	v_rcp_f32_e32 v165, v165
	v_rcp_f32_e32 v166, v166
	v_rcp_f32_e32 v167, v167
	v_rcp_f32_e32 v168, v168
	v_rcp_f32_e32 v169, v169
	v_rcp_f32_e32 v170, v170
	v_rcp_f32_e32 v171, v171
	v_cvt_pk_bf16_f32 v172, v164, v165
	v_cvt_pk_bf16_f32 v173, v166, v167
	v_cvt_pk_bf16_f32 v174, v168, v169
	v_cvt_pk_bf16_f32 v175, v170, v171
	s_add_u32 s46, s46, 0x28000
	s_addc_u32 s47, s47, 0
	global_store_dwordx4 v130, v[172:175], s[46:47] nt
	v_add_f32_e32 v180, v54, v156
	v_add_f32_e32 v181, v55, v157
	v_add_f32_e32 v182, v56, v158
	v_add_f32_e32 v183, v57, v159
	v_add_f32_e32 v184, v50, v160
	v_add_f32_e32 v185, v51, v161
	v_add_f32_e32 v186, v52, v162
	v_add_f32_e32 v187, v53, v163
	v_mul_f32_e32 v180, 0xbfb8aa3b, v180
	v_mul_f32_e32 v181, 0xbfb8aa3b, v181
	v_mul_f32_e32 v182, 0xbfb8aa3b, v182
	v_mul_f32_e32 v183, 0xbfb8aa3b, v183
	v_mul_f32_e32 v184, 0xbfb8aa3b, v184
	v_mul_f32_e32 v185, 0xbfb8aa3b, v185
	v_mul_f32_e32 v186, 0xbfb8aa3b, v186
	v_mul_f32_e32 v187, 0xbfb8aa3b, v187
	v_exp_f32_e32 v180, v180
	v_exp_f32_e32 v181, v181
	v_exp_f32_e32 v182, v182
	v_exp_f32_e32 v183, v183
	v_exp_f32_e32 v184, v184
	v_exp_f32_e32 v185, v185
	v_exp_f32_e32 v186, v186
	v_exp_f32_e32 v187, v187
	v_add_f32_e32 v180, 1.0, v180
	v_add_f32_e32 v181, 1.0, v181
	v_add_f32_e32 v182, 1.0, v182
	v_add_f32_e32 v183, 1.0, v183
	v_add_f32_e32 v184, 1.0, v184
	v_add_f32_e32 v185, 1.0, v185
	v_add_f32_e32 v186, 1.0, v186
	v_add_f32_e32 v187, 1.0, v187
	v_rcp_f32_e32 v180, v180
	v_rcp_f32_e32 v181, v181
	v_rcp_f32_e32 v182, v182
	v_rcp_f32_e32 v183, v183
	v_rcp_f32_e32 v184, v184
	v_rcp_f32_e32 v185, v185
	v_rcp_f32_e32 v186, v186
	v_rcp_f32_e32 v187, v187
	v_cvt_pk_bf16_f32 v188, v180, v181
	v_cvt_pk_bf16_f32 v189, v182, v183
	v_cvt_pk_bf16_f32 v190, v184, v185
	v_cvt_pk_bf16_f32 v191, v186, v187
	global_store_dwordx4 v130, v[188:191], s[46:47] offset:256 nt
	v_add_f32_e32 v164, v46, v132
	v_add_f32_e32 v165, v47, v133
	v_add_f32_e32 v166, v48, v134
	v_add_f32_e32 v167, v49, v135
	v_add_f32_e32 v168, v42, v152
	v_add_f32_e32 v169, v43, v153
	v_add_f32_e32 v170, v44, v154
	v_add_f32_e32 v171, v45, v155
	v_mul_f32_e32 v164, 0xbfb8aa3b, v164
	v_mul_f32_e32 v165, 0xbfb8aa3b, v165
	v_mul_f32_e32 v166, 0xbfb8aa3b, v166
	v_mul_f32_e32 v167, 0xbfb8aa3b, v167
	v_mul_f32_e32 v168, 0xbfb8aa3b, v168
	v_mul_f32_e32 v169, 0xbfb8aa3b, v169
	v_mul_f32_e32 v170, 0xbfb8aa3b, v170
	v_mul_f32_e32 v171, 0xbfb8aa3b, v171
	v_exp_f32_e32 v164, v164
	v_exp_f32_e32 v165, v165
	v_exp_f32_e32 v166, v166
	v_exp_f32_e32 v167, v167
	v_exp_f32_e32 v168, v168
	v_exp_f32_e32 v169, v169
	v_exp_f32_e32 v170, v170
	v_exp_f32_e32 v171, v171
	v_add_f32_e32 v164, 1.0, v164
	v_add_f32_e32 v165, 1.0, v165
	v_add_f32_e32 v166, 1.0, v166
	v_add_f32_e32 v167, 1.0, v167
	v_add_f32_e32 v168, 1.0, v168
	v_add_f32_e32 v169, 1.0, v169
	v_add_f32_e32 v170, 1.0, v170
	v_add_f32_e32 v171, 1.0, v171
	v_rcp_f32_e32 v164, v164
	v_rcp_f32_e32 v165, v165
	v_rcp_f32_e32 v166, v166
	v_rcp_f32_e32 v167, v167
	v_rcp_f32_e32 v168, v168
	v_rcp_f32_e32 v169, v169
	v_rcp_f32_e32 v170, v170
	v_rcp_f32_e32 v171, v171
	v_cvt_pk_bf16_f32 v172, v164, v165
	v_cvt_pk_bf16_f32 v173, v166, v167
	v_cvt_pk_bf16_f32 v174, v168, v169
	v_cvt_pk_bf16_f32 v175, v170, v171
	s_add_u32 s46, s46, 0x8000
	s_addc_u32 s47, s47, 0
	global_store_dwordx4 v130, v[172:175], s[46:47] nt
	v_add_f32_e32 v180, v38, v156
	v_add_f32_e32 v181, v39, v157
	v_add_f32_e32 v182, v40, v158
	v_add_f32_e32 v183, v41, v159
	v_add_f32_e32 v184, v34, v160
	v_add_f32_e32 v185, v35, v161
	v_add_f32_e32 v186, v36, v162
	v_add_f32_e32 v187, v37, v163
	v_mul_f32_e32 v180, 0xbfb8aa3b, v180
	v_mul_f32_e32 v181, 0xbfb8aa3b, v181
	v_mul_f32_e32 v182, 0xbfb8aa3b, v182
	v_mul_f32_e32 v183, 0xbfb8aa3b, v183
	v_mul_f32_e32 v184, 0xbfb8aa3b, v184
	v_mul_f32_e32 v185, 0xbfb8aa3b, v185
	v_mul_f32_e32 v186, 0xbfb8aa3b, v186
	v_mul_f32_e32 v187, 0xbfb8aa3b, v187
	v_exp_f32_e32 v180, v180
	v_exp_f32_e32 v181, v181
	v_exp_f32_e32 v182, v182
	v_exp_f32_e32 v183, v183
	v_exp_f32_e32 v184, v184
	v_exp_f32_e32 v185, v185
	v_exp_f32_e32 v186, v186
	v_exp_f32_e32 v187, v187
	v_add_f32_e32 v180, 1.0, v180
	v_add_f32_e32 v181, 1.0, v181
	v_add_f32_e32 v182, 1.0, v182
	v_add_f32_e32 v183, 1.0, v183
	v_add_f32_e32 v184, 1.0, v184
	v_add_f32_e32 v185, 1.0, v185
	v_add_f32_e32 v186, 1.0, v186
	v_add_f32_e32 v187, 1.0, v187
	v_rcp_f32_e32 v180, v180
	v_rcp_f32_e32 v181, v181
	v_rcp_f32_e32 v182, v182
	v_rcp_f32_e32 v183, v183
	v_rcp_f32_e32 v184, v184
	v_rcp_f32_e32 v185, v185
	v_rcp_f32_e32 v186, v186
	v_rcp_f32_e32 v187, v187
	v_cvt_pk_bf16_f32 v188, v180, v181
	v_cvt_pk_bf16_f32 v189, v182, v183
	v_cvt_pk_bf16_f32 v190, v184, v185
	v_cvt_pk_bf16_f32 v191, v186, v187
	global_store_dwordx4 v130, v[188:191], s[46:47] offset:256 nt
	v_add_f32_e32 v164, v30, v132
	v_add_f32_e32 v165, v31, v133
	v_add_f32_e32 v166, v32, v134
	v_add_f32_e32 v167, v33, v135
	v_add_f32_e32 v168, v26, v152
	v_add_f32_e32 v169, v27, v153
	v_add_f32_e32 v170, v28, v154
	v_add_f32_e32 v171, v29, v155
	v_mul_f32_e32 v164, 0xbfb8aa3b, v164
	v_mul_f32_e32 v165, 0xbfb8aa3b, v165
	v_mul_f32_e32 v166, 0xbfb8aa3b, v166
	v_mul_f32_e32 v167, 0xbfb8aa3b, v167
	v_mul_f32_e32 v168, 0xbfb8aa3b, v168
	v_mul_f32_e32 v169, 0xbfb8aa3b, v169
	v_mul_f32_e32 v170, 0xbfb8aa3b, v170
	v_mul_f32_e32 v171, 0xbfb8aa3b, v171
	v_exp_f32_e32 v164, v164
	v_exp_f32_e32 v165, v165
	v_exp_f32_e32 v166, v166
	v_exp_f32_e32 v167, v167
	v_exp_f32_e32 v168, v168
	v_exp_f32_e32 v169, v169
	v_exp_f32_e32 v170, v170
	v_exp_f32_e32 v171, v171
	v_add_f32_e32 v164, 1.0, v164
	v_add_f32_e32 v165, 1.0, v165
	v_add_f32_e32 v166, 1.0, v166
	v_add_f32_e32 v167, 1.0, v167
	v_add_f32_e32 v168, 1.0, v168
	v_add_f32_e32 v169, 1.0, v169
	v_add_f32_e32 v170, 1.0, v170
	v_add_f32_e32 v171, 1.0, v171
	v_rcp_f32_e32 v164, v164
	v_rcp_f32_e32 v165, v165
	v_rcp_f32_e32 v166, v166
	v_rcp_f32_e32 v167, v167
	v_rcp_f32_e32 v168, v168
	v_rcp_f32_e32 v169, v169
	v_rcp_f32_e32 v170, v170
	v_rcp_f32_e32 v171, v171
	v_cvt_pk_bf16_f32 v172, v164, v165
	v_cvt_pk_bf16_f32 v173, v166, v167
	v_cvt_pk_bf16_f32 v174, v168, v169
	v_cvt_pk_bf16_f32 v175, v170, v171
	s_add_u32 s46, s46, 0x8000
	s_addc_u32 s47, s47, 0
	global_store_dwordx4 v130, v[172:175], s[46:47] nt
	v_add_f32_e32 v180, v22, v156
	v_add_f32_e32 v181, v23, v157
	v_add_f32_e32 v182, v24, v158
	v_add_f32_e32 v183, v25, v159
	v_add_f32_e32 v184, v18, v160
	v_add_f32_e32 v185, v19, v161
	v_add_f32_e32 v186, v20, v162
	v_add_f32_e32 v187, v21, v163
	v_mul_f32_e32 v180, 0xbfb8aa3b, v180
	v_mul_f32_e32 v181, 0xbfb8aa3b, v181
	v_mul_f32_e32 v182, 0xbfb8aa3b, v182
	v_mul_f32_e32 v183, 0xbfb8aa3b, v183
	v_mul_f32_e32 v184, 0xbfb8aa3b, v184
	v_mul_f32_e32 v185, 0xbfb8aa3b, v185
	v_mul_f32_e32 v186, 0xbfb8aa3b, v186
	v_mul_f32_e32 v187, 0xbfb8aa3b, v187
	v_exp_f32_e32 v180, v180
	v_exp_f32_e32 v181, v181
	v_exp_f32_e32 v182, v182
	v_exp_f32_e32 v183, v183
	v_exp_f32_e32 v184, v184
	v_exp_f32_e32 v185, v185
	v_exp_f32_e32 v186, v186
	v_exp_f32_e32 v187, v187
	v_add_f32_e32 v180, 1.0, v180
	v_add_f32_e32 v181, 1.0, v181
	v_add_f32_e32 v182, 1.0, v182
	v_add_f32_e32 v183, 1.0, v183
	v_add_f32_e32 v184, 1.0, v184
	v_add_f32_e32 v185, 1.0, v185
	v_add_f32_e32 v186, 1.0, v186
	v_add_f32_e32 v187, 1.0, v187
	v_rcp_f32_e32 v180, v180
	v_rcp_f32_e32 v181, v181
	v_rcp_f32_e32 v182, v182
	v_rcp_f32_e32 v183, v183
	v_rcp_f32_e32 v184, v184
	v_rcp_f32_e32 v185, v185
	v_rcp_f32_e32 v186, v186
	v_rcp_f32_e32 v187, v187
	v_cvt_pk_bf16_f32 v188, v180, v181
	v_cvt_pk_bf16_f32 v189, v182, v183
	v_cvt_pk_bf16_f32 v190, v184, v185
	v_cvt_pk_bf16_f32 v191, v186, v187
	global_store_dwordx4 v130, v[188:191], s[46:47] offset:256 nt
	v_add_f32_e32 v164, v14, v132
	v_add_f32_e32 v165, v15, v133
	v_add_f32_e32 v166, v16, v134
	v_add_f32_e32 v167, v17, v135
	v_add_f32_e32 v168, v10, v152
	v_add_f32_e32 v169, v11, v153
	v_add_f32_e32 v170, v12, v154
	v_add_f32_e32 v171, v13, v155
	v_mul_f32_e32 v164, 0xbfb8aa3b, v164
	v_mul_f32_e32 v165, 0xbfb8aa3b, v165
	v_mul_f32_e32 v166, 0xbfb8aa3b, v166
	v_mul_f32_e32 v167, 0xbfb8aa3b, v167
	v_mul_f32_e32 v168, 0xbfb8aa3b, v168
	v_mul_f32_e32 v169, 0xbfb8aa3b, v169
	v_mul_f32_e32 v170, 0xbfb8aa3b, v170
	v_mul_f32_e32 v171, 0xbfb8aa3b, v171
	v_exp_f32_e32 v164, v164
	v_exp_f32_e32 v165, v165
	v_exp_f32_e32 v166, v166
	v_exp_f32_e32 v167, v167
	v_exp_f32_e32 v168, v168
	v_exp_f32_e32 v169, v169
	v_exp_f32_e32 v170, v170
	v_exp_f32_e32 v171, v171
	v_add_f32_e32 v164, 1.0, v164
	v_add_f32_e32 v165, 1.0, v165
	v_add_f32_e32 v166, 1.0, v166
	v_add_f32_e32 v167, 1.0, v167
	v_add_f32_e32 v168, 1.0, v168
	v_add_f32_e32 v169, 1.0, v169
	v_add_f32_e32 v170, 1.0, v170
	v_add_f32_e32 v171, 1.0, v171
	v_rcp_f32_e32 v164, v164
	v_rcp_f32_e32 v165, v165
	v_rcp_f32_e32 v166, v166
	v_rcp_f32_e32 v167, v167
	v_rcp_f32_e32 v168, v168
	v_rcp_f32_e32 v169, v169
	v_rcp_f32_e32 v170, v170
	v_rcp_f32_e32 v171, v171
	v_cvt_pk_bf16_f32 v172, v164, v165
	v_cvt_pk_bf16_f32 v173, v166, v167
	v_cvt_pk_bf16_f32 v174, v168, v169
	v_cvt_pk_bf16_f32 v175, v170, v171
	s_add_u32 s46, s46, 0x8000
	s_addc_u32 s47, s47, 0
	global_store_dwordx4 v130, v[172:175], s[46:47] nt
	v_add_f32_e32 v180, v6, v156
	v_add_f32_e32 v181, v7, v157
	v_add_f32_e32 v182, v8, v158
	v_add_f32_e32 v183, v9, v159
	v_add_f32_e32 v184, v2, v160
	v_add_f32_e32 v185, v3, v161
	v_add_f32_e32 v186, v4, v162
	v_add_f32_e32 v187, v5, v163
	v_mul_f32_e32 v180, 0xbfb8aa3b, v180
	v_mul_f32_e32 v181, 0xbfb8aa3b, v181
	v_mul_f32_e32 v182, 0xbfb8aa3b, v182
	v_mul_f32_e32 v183, 0xbfb8aa3b, v183
	v_mul_f32_e32 v184, 0xbfb8aa3b, v184
	v_mul_f32_e32 v185, 0xbfb8aa3b, v185
	v_mul_f32_e32 v186, 0xbfb8aa3b, v186
	v_mul_f32_e32 v187, 0xbfb8aa3b, v187
	v_exp_f32_e32 v180, v180
	v_exp_f32_e32 v181, v181
	v_exp_f32_e32 v182, v182
	v_exp_f32_e32 v183, v183
	v_exp_f32_e32 v184, v184
	v_exp_f32_e32 v185, v185
	v_exp_f32_e32 v186, v186
	v_exp_f32_e32 v187, v187
	v_add_f32_e32 v180, 1.0, v180
	v_add_f32_e32 v181, 1.0, v181
	v_add_f32_e32 v182, 1.0, v182
	v_add_f32_e32 v183, 1.0, v183
	v_add_f32_e32 v184, 1.0, v184
	v_add_f32_e32 v185, 1.0, v185
	v_add_f32_e32 v186, 1.0, v186
	v_add_f32_e32 v187, 1.0, v187
	v_rcp_f32_e32 v180, v180
	v_rcp_f32_e32 v181, v181
	v_rcp_f32_e32 v182, v182
	v_rcp_f32_e32 v183, v183
	v_rcp_f32_e32 v184, v184
	v_rcp_f32_e32 v185, v185
	v_rcp_f32_e32 v186, v186
	v_rcp_f32_e32 v187, v187
	v_cvt_pk_bf16_f32 v188, v180, v181
	v_cvt_pk_bf16_f32 v189, v182, v183
	v_cvt_pk_bf16_f32 v190, v184, v185
	v_cvt_pk_bf16_f32 v191, v186, v187
	global_store_dwordx4 v130, v[188:191], s[46:47] offset:256 nt
	s_branch .LBB0_1251
.Lepi_projn_lat:
	s_lshl_b32 s9, s9, 8
	s_add_i32 s9, s9, s60
	s_cmp_eq_u32 s8, 14
	s_cbranch_scc1 .Lepi_lat_cq
	s_cmp_eq_u32 s26, 0
	s_cbranch_scc1 .Lepi_lat_kv_kpe
	s_cmp_eq_u32 s26, 32
	s_cbranch_scc1 .Lepi_lat_kv_alr
.Lepi_lat_kv:
	v_readlane_b32 s68, v255, 36
	v_readlane_b32 s69, v255, 37
	s_lshl_b32 s78, s26, 2
	s_nop 1
	s_add_u32 s68, s68, s78
	s_addc_u32 s69, s69, 0
	v_lshlrev_b32_e32 v131, 2, v176
	global_load_dwordx4 v[134:137], v131, s[68:69] offset:0
	global_load_dwordx4 v[152:155], v131, s[68:69] offset:16
	s_mul_i32 s8, s9, 256
	s_lshl_b32 s78, s26, 1
	s_add_i32 s8, s8, s78
	s_add_u32 s46, s36, s8
	s_addc_u32 s47, s37, 0
	s_add_u32 s46, s46, 0x1e600000
	s_addc_u32 s47, s47, 0
	s_lshl_b32 s8, s9, 2
	s_add_u32 s38, s36, s8
	s_addc_u32 s39, s37, 0
	s_add_u32 s38, s38, 0x1140000
	s_addc_u32 s39, s39, 0
	v_mul_u32_u24_e32 v130, 256, v1
	v_lshl_add_u32 v130, v176, 1, v130
	v_lshlrev_b32_e32 v132, 2, v1
	v_cmp_eq_u32_e64 s[68:69], 0, v176
	s_waitcnt vmcnt(0)
	v_mul_f32_e32 v184, v127, v127
	v_mul_f32_e32 v185, v129, v129
	v_mul_f32_e32 v186, v123, v123
	v_mul_f32_e32 v187, v125, v125
	v_fmac_f32_e32 v184, v126, v126
	v_fmac_f32_e32 v185, v128, v128
	v_fmac_f32_e32 v186, v122, v122
	v_fmac_f32_e32 v187, v124, v124
	v_pk_mul_f32 v[156:157], v[126:127], v[134:135]
	v_pk_mul_f32 v[158:159], v[128:129], v[136:137]
	v_pk_mul_f32 v[160:161], v[122:123], v[152:153]
	v_pk_mul_f32 v[162:163], v[124:125], v[154:155]
	v_add_f32_e32 v184, v184, v185
	v_add_f32_e32 v184, v186, v184
	v_add_f32_e32 v192, v187, v184
	v_cvt_pk_bf16_f32 v172, v156, v157
	v_cvt_pk_bf16_f32 v173, v158, v159
	v_cvt_pk_bf16_f32 v174, v160, v161
	v_cvt_pk_bf16_f32 v175, v162, v163
	v_mov_b32_e32 v193, v192
	global_store_dwordx4 v130, v[172:175], s[46:47]
	s_nop 1
	v_permlane16_swap_b32_e32 v192, v193
	v_add_f32_e32 v192, v192, v193
	v_mov_b32_e32 v193, v192
	s_nop 1
	v_permlane32_swap_b32_e32 v192, v193
	v_add_f32_e32 v192, v192, v193
	s_mov_b64 s[74:75], exec
	s_and_b64 exec, exec, s[68:69]
	global_atomic_add_f32 v132, v192, s[38:39]
	s_mov_b64 exec, s[74:75]
	v_mul_f32_e32 v184, v111, v111
	v_mul_f32_e32 v185, v113, v113
	v_mul_f32_e32 v186, v107, v107
	v_mul_f32_e32 v187, v109, v109
	v_fmac_f32_e32 v184, v110, v110
	v_fmac_f32_e32 v185, v112, v112
	v_fmac_f32_e32 v186, v106, v106
	v_fmac_f32_e32 v187, v108, v108
	v_pk_mul_f32 v[156:157], v[110:111], v[134:135]
	v_pk_mul_f32 v[158:159], v[112:113], v[136:137]
	v_pk_mul_f32 v[160:161], v[106:107], v[152:153]
	v_pk_mul_f32 v[162:163], v[108:109], v[154:155]
	v_add_f32_e32 v184, v184, v185
	v_add_f32_e32 v184, v186, v184
	v_add_f32_e32 v192, v187, v184
	v_cvt_pk_bf16_f32 v172, v156, v157
	v_cvt_pk_bf16_f32 v173, v158, v159
	v_cvt_pk_bf16_f32 v174, v160, v161
	v_cvt_pk_bf16_f32 v175, v162, v163
	v_mov_b32_e32 v193, v192
	s_add_u32 s46, s46, 0x1000
	s_addc_u32 s47, s47, 0
	s_add_u32 s38, s38, 0x40
	s_addc_u32 s39, s39, 0
	global_store_dwordx4 v130, v[172:175], s[46:47]
	s_nop 1
	v_permlane16_swap_b32_e32 v192, v193
	v_add_f32_e32 v192, v192, v193
	v_mov_b32_e32 v193, v192
	s_nop 1
	v_permlane32_swap_b32_e32 v192, v193
	v_add_f32_e32 v192, v192, v193
	s_mov_b64 s[74:75], exec
	s_and_b64 exec, exec, s[68:69]
	global_atomic_add_f32 v132, v192, s[38:39]
	s_mov_b64 exec, s[74:75]
	v_mul_f32_e32 v184, v95, v95
	v_mul_f32_e32 v185, v97, v97
	v_mul_f32_e32 v186, v91, v91
	v_mul_f32_e32 v187, v93, v93
	v_fmac_f32_e32 v184, v94, v94
	v_fmac_f32_e32 v185, v96, v96
	v_fmac_f32_e32 v186, v90, v90
	v_fmac_f32_e32 v187, v92, v92
	v_pk_mul_f32 v[156:157], v[94:95], v[134:135]
	v_pk_mul_f32 v[158:159], v[96:97], v[136:137]
	v_pk_mul_f32 v[160:161], v[90:91], v[152:153]
	v_pk_mul_f32 v[162:163], v[92:93], v[154:155]
	v_add_f32_e32 v184, v184, v185
	v_add_f32_e32 v184, v186, v184
	v_add_f32_e32 v192, v187, v184
	v_cvt_pk_bf16_f32 v172, v156, v157
	v_cvt_pk_bf16_f32 v173, v158, v159
	v_cvt_pk_bf16_f32 v174, v160, v161
	v_cvt_pk_bf16_f32 v175, v162, v163
	v_mov_b32_e32 v193, v192
	s_add_u32 s46, s46, 0x1000
	s_addc_u32 s47, s47, 0
	s_add_u32 s38, s38, 0x40
	s_addc_u32 s39, s39, 0
	global_store_dwordx4 v130, v[172:175], s[46:47]
	s_nop 1
	v_permlane16_swap_b32_e32 v192, v193
	v_add_f32_e32 v192, v192, v193
	v_mov_b32_e32 v193, v192
	s_nop 1
	v_permlane32_swap_b32_e32 v192, v193
	v_add_f32_e32 v192, v192, v193
	s_mov_b64 s[74:75], exec
	s_and_b64 exec, exec, s[68:69]
	global_atomic_add_f32 v132, v192, s[38:39]
	s_mov_b64 exec, s[74:75]
	v_mul_f32_e32 v184, v79, v79
	v_mul_f32_e32 v185, v81, v81
	v_mul_f32_e32 v186, v75, v75
	v_mul_f32_e32 v187, v77, v77
	v_fmac_f32_e32 v184, v78, v78
	v_fmac_f32_e32 v185, v80, v80
	v_fmac_f32_e32 v186, v74, v74
	v_fmac_f32_e32 v187, v76, v76
	v_pk_mul_f32 v[156:157], v[78:79], v[134:135]
	v_pk_mul_f32 v[158:159], v[80:81], v[136:137]
	v_pk_mul_f32 v[160:161], v[74:75], v[152:153]
	v_pk_mul_f32 v[162:163], v[76:77], v[154:155]
	v_add_f32_e32 v184, v184, v185
	v_add_f32_e32 v184, v186, v184
	v_add_f32_e32 v192, v187, v184
	v_cvt_pk_bf16_f32 v172, v156, v157
	v_cvt_pk_bf16_f32 v173, v158, v159
	v_cvt_pk_bf16_f32 v174, v160, v161
	v_cvt_pk_bf16_f32 v175, v162, v163
	v_mov_b32_e32 v193, v192
	s_add_u32 s46, s46, 0x1000
	s_addc_u32 s47, s47, 0
	s_add_u32 s38, s38, 0x40
	s_addc_u32 s39, s39, 0
	global_store_dwordx4 v130, v[172:175], s[46:47]
	s_nop 1
	v_permlane16_swap_b32_e32 v192, v193
	v_add_f32_e32 v192, v192, v193
	v_mov_b32_e32 v193, v192
	s_nop 1
	v_permlane32_swap_b32_e32 v192, v193
	v_add_f32_e32 v192, v192, v193
	s_mov_b64 s[74:75], exec
	s_and_b64 exec, exec, s[68:69]
	global_atomic_add_f32 v132, v192, s[38:39]
	s_mov_b64 exec, s[74:75]
	v_mul_f32_e32 v184, v63, v63
	v_mul_f32_e32 v185, v65, v65
	v_mul_f32_e32 v186, v59, v59
	v_mul_f32_e32 v187, v61, v61
	v_fmac_f32_e32 v184, v62, v62
	v_fmac_f32_e32 v185, v64, v64
	v_fmac_f32_e32 v186, v58, v58
	v_fmac_f32_e32 v187, v60, v60
	v_pk_mul_f32 v[156:157], v[62:63], v[134:135]
	v_pk_mul_f32 v[158:159], v[64:65], v[136:137]
	v_pk_mul_f32 v[160:161], v[58:59], v[152:153]
	v_pk_mul_f32 v[162:163], v[60:61], v[154:155]
	v_add_f32_e32 v184, v184, v185
	v_add_f32_e32 v184, v186, v184
	v_add_f32_e32 v192, v187, v184
	v_cvt_pk_bf16_f32 v172, v156, v157
	v_cvt_pk_bf16_f32 v173, v158, v159
	v_cvt_pk_bf16_f32 v174, v160, v161
	v_cvt_pk_bf16_f32 v175, v162, v163
	v_mov_b32_e32 v193, v192
	s_add_u32 s46, s46, 0x5000
	s_addc_u32 s47, s47, 0
	s_add_u32 s38, s38, 0x140
	s_addc_u32 s39, s39, 0
	global_store_dwordx4 v130, v[172:175], s[46:47]
	s_nop 1
	v_permlane16_swap_b32_e32 v192, v193
	v_add_f32_e32 v192, v192, v193
	v_mov_b32_e32 v193, v192
	s_nop 1
	v_permlane32_swap_b32_e32 v192, v193
	v_add_f32_e32 v192, v192, v193
	s_mov_b64 s[74:75], exec
	s_and_b64 exec, exec, s[68:69]
	global_atomic_add_f32 v132, v192, s[38:39]
	s_mov_b64 exec, s[74:75]
	v_mul_f32_e32 v184, v47, v47
	v_mul_f32_e32 v185, v49, v49
	v_mul_f32_e32 v186, v43, v43
	v_mul_f32_e32 v187, v45, v45
	v_fmac_f32_e32 v184, v46, v46
	v_fmac_f32_e32 v185, v48, v48
	v_fmac_f32_e32 v186, v42, v42
	v_fmac_f32_e32 v187, v44, v44
	v_pk_mul_f32 v[156:157], v[46:47], v[134:135]
	v_pk_mul_f32 v[158:159], v[48:49], v[136:137]
	v_pk_mul_f32 v[160:161], v[42:43], v[152:153]
	v_pk_mul_f32 v[162:163], v[44:45], v[154:155]
	v_add_f32_e32 v184, v184, v185
	v_add_f32_e32 v184, v186, v184
	v_add_f32_e32 v192, v187, v184
	v_cvt_pk_bf16_f32 v172, v156, v157
	v_cvt_pk_bf16_f32 v173, v158, v159
	v_cvt_pk_bf16_f32 v174, v160, v161
	v_cvt_pk_bf16_f32 v175, v162, v163
	v_mov_b32_e32 v193, v192
	s_add_u32 s46, s46, 0x1000
	s_addc_u32 s47, s47, 0
	s_add_u32 s38, s38, 0x40
	s_addc_u32 s39, s39, 0
	global_store_dwordx4 v130, v[172:175], s[46:47]
	s_nop 1
	v_permlane16_swap_b32_e32 v192, v193
	v_add_f32_e32 v192, v192, v193
	v_mov_b32_e32 v193, v192
	s_nop 1
	v_permlane32_swap_b32_e32 v192, v193
	v_add_f32_e32 v192, v192, v193
	s_mov_b64 s[74:75], exec
	s_and_b64 exec, exec, s[68:69]
	global_atomic_add_f32 v132, v192, s[38:39]
	s_mov_b64 exec, s[74:75]
	v_mul_f32_e32 v184, v31, v31
	v_mul_f32_e32 v185, v33, v33
	v_mul_f32_e32 v186, v27, v27
	v_mul_f32_e32 v187, v29, v29
	v_fmac_f32_e32 v184, v30, v30
	v_fmac_f32_e32 v185, v32, v32
	v_fmac_f32_e32 v186, v26, v26
	v_fmac_f32_e32 v187, v28, v28
	v_pk_mul_f32 v[156:157], v[30:31], v[134:135]
	v_pk_mul_f32 v[158:159], v[32:33], v[136:137]
	v_pk_mul_f32 v[160:161], v[26:27], v[152:153]
	v_pk_mul_f32 v[162:163], v[28:29], v[154:155]
	v_add_f32_e32 v184, v184, v185
	v_add_f32_e32 v184, v186, v184
	v_add_f32_e32 v192, v187, v184
	v_cvt_pk_bf16_f32 v172, v156, v157
	v_cvt_pk_bf16_f32 v173, v158, v159
	v_cvt_pk_bf16_f32 v174, v160, v161
	v_cvt_pk_bf16_f32 v175, v162, v163
	v_mov_b32_e32 v193, v192
	s_add_u32 s46, s46, 0x1000
	s_addc_u32 s47, s47, 0
	s_add_u32 s38, s38, 0x40
	s_addc_u32 s39, s39, 0
	global_store_dwordx4 v130, v[172:175], s[46:47]
	s_nop 1
	v_permlane16_swap_b32_e32 v192, v193
	v_add_f32_e32 v192, v192, v193
	v_mov_b32_e32 v193, v192
	s_nop 1
	v_permlane32_swap_b32_e32 v192, v193
	v_add_f32_e32 v192, v192, v193
	s_mov_b64 s[74:75], exec
	s_and_b64 exec, exec, s[68:69]
	global_atomic_add_f32 v132, v192, s[38:39]
	s_mov_b64 exec, s[74:75]
	v_mul_f32_e32 v184, v15, v15
	v_mul_f32_e32 v185, v17, v17
	v_mul_f32_e32 v186, v11, v11
	v_mul_f32_e32 v187, v13, v13
	v_fmac_f32_e32 v184, v14, v14
	v_fmac_f32_e32 v185, v16, v16
	v_fmac_f32_e32 v186, v10, v10
	v_fmac_f32_e32 v187, v12, v12
	v_pk_mul_f32 v[156:157], v[14:15], v[134:135]
	v_pk_mul_f32 v[158:159], v[16:17], v[136:137]
	v_pk_mul_f32 v[160:161], v[10:11], v[152:153]
	v_pk_mul_f32 v[162:163], v[12:13], v[154:155]
	v_add_f32_e32 v184, v184, v185
	v_add_f32_e32 v184, v186, v184
	v_add_f32_e32 v192, v187, v184
	v_cvt_pk_bf16_f32 v172, v156, v157
	v_cvt_pk_bf16_f32 v173, v158, v159
	v_cvt_pk_bf16_f32 v174, v160, v161
	v_cvt_pk_bf16_f32 v175, v162, v163
	v_mov_b32_e32 v193, v192
	s_add_u32 s46, s46, 0x1000
	s_addc_u32 s47, s47, 0
	s_add_u32 s38, s38, 0x40
	s_addc_u32 s39, s39, 0
	global_store_dwordx4 v130, v[172:175], s[46:47]
	s_nop 1
	v_permlane16_swap_b32_e32 v192, v193
	v_add_f32_e32 v192, v192, v193
	v_mov_b32_e32 v193, v192
	s_nop 1
	v_permlane32_swap_b32_e32 v192, v193
	v_add_f32_e32 v192, v192, v193
	s_mov_b64 s[74:75], exec
	s_and_b64 exec, exec, s[68:69]
	global_atomic_add_f32 v132, v192, s[38:39]
	s_mov_b64 exec, s[74:75]
	s_branch .LBB0_1251
.Lepi_lat_kv_kpe:
	v_readlane_b32 s68, v255, 36
	v_readlane_b32 s69, v255, 37
	s_lshl_b32 s78, s26, 2
	s_nop 1
	s_add_u32 s68, s68, s78
	s_addc_u32 s69, s69, 0
	v_lshlrev_b32_e32 v131, 2, v176
	global_load_dwordx4 v[134:137], v131, s[68:69] offset:0
	global_load_dwordx4 v[152:155], v131, s[68:69] offset:16
	s_mul_i32 s8, s9, 256
	s_lshl_b32 s78, s26, 1
	s_add_i32 s8, s8, s78
	s_add_u32 s46, s36, s8
	s_addc_u32 s47, s37, 0
	s_add_u32 s46, s46, 0x1e600000
	s_addc_u32 s47, s47, 0
	s_lshl_b32 s8, s9, 2
	s_add_u32 s38, s36, s8
	s_addc_u32 s39, s37, 0
	s_add_u32 s38, s38, 0x1140000
	s_addc_u32 s39, s39, 0
	v_mul_u32_u24_e32 v130, 256, v1
	v_lshl_add_u32 v130, v176, 1, v130
	v_lshlrev_b32_e32 v132, 2, v1
	v_cmp_eq_u32_e64 s[68:69], 0, v176
	s_mul_i32 s8, s9, 128
	s_add_u32 s48, s36, s8
	s_addc_u32 s41, s37, 0
	v_mul_u32_u24_e32 v133, 128, v1
	v_lshl_add_u32 v133, v176, 2, v133
	s_waitcnt vmcnt(0)
	v_mul_f32_e32 v184, v127, v127
	v_mul_f32_e32 v185, v129, v129
	v_mul_f32_e32 v186, v123, v123
	v_mul_f32_e32 v187, v125, v125
	v_fmac_f32_e32 v184, v126, v126
	v_fmac_f32_e32 v185, v128, v128
	v_fmac_f32_e32 v186, v122, v122
	v_fmac_f32_e32 v187, v124, v124
	v_pk_mul_f32 v[156:157], v[126:127], v[134:135]
	v_pk_mul_f32 v[158:159], v[128:129], v[136:137]
	v_pk_mul_f32 v[160:161], v[122:123], v[152:153]
	v_pk_mul_f32 v[162:163], v[124:125], v[154:155]
	v_add_f32_e32 v184, v184, v185
	v_add_f32_e32 v184, v186, v184
	v_add_f32_e32 v192, v187, v184
	v_cvt_pk_bf16_f32 v172, v156, v157
	v_cvt_pk_bf16_f32 v173, v158, v159
	v_cvt_pk_bf16_f32 v174, v160, v161
	v_cvt_pk_bf16_f32 v175, v162, v163
	v_mov_b32_e32 v193, v192
	global_store_dwordx4 v130, v[172:175], s[46:47]
	s_nop 1
	v_permlane16_swap_b32_e32 v192, v193
	v_add_f32_e32 v192, v192, v193
	v_mov_b32_e32 v193, v192
	s_nop 1
	v_permlane32_swap_b32_e32 v192, v193
	v_add_f32_e32 v192, v192, v193
	s_mov_b64 s[74:75], exec
	s_and_b64 exec, exec, s[68:69]
	global_atomic_add_f32 v132, v192, s[38:39]
	s_mov_b64 exec, s[74:75]
	s_add_u32 s74, s48, 0xb00000
	s_addc_u32 s75, s41, 0
	global_store_dwordx4 v133, v[118:121], s[74:75]
	global_store_dwordx4 v133, v[114:117], s[74:75] offset:16
	v_mul_f32_e32 v184, v111, v111
	v_mul_f32_e32 v185, v113, v113
	v_mul_f32_e32 v186, v107, v107
	v_mul_f32_e32 v187, v109, v109
	v_fmac_f32_e32 v184, v110, v110
	v_fmac_f32_e32 v185, v112, v112
	v_fmac_f32_e32 v186, v106, v106
	v_fmac_f32_e32 v187, v108, v108
	v_pk_mul_f32 v[156:157], v[110:111], v[134:135]
	v_pk_mul_f32 v[158:159], v[112:113], v[136:137]
	v_pk_mul_f32 v[160:161], v[106:107], v[152:153]
	v_pk_mul_f32 v[162:163], v[108:109], v[154:155]
	v_add_f32_e32 v184, v184, v185
	v_add_f32_e32 v184, v186, v184
	v_add_f32_e32 v192, v187, v184
	v_cvt_pk_bf16_f32 v172, v156, v157
	v_cvt_pk_bf16_f32 v173, v158, v159
	v_cvt_pk_bf16_f32 v174, v160, v161
	v_cvt_pk_bf16_f32 v175, v162, v163
	v_mov_b32_e32 v193, v192
	s_add_u32 s46, s46, 0x1000
	s_addc_u32 s47, s47, 0
	s_add_u32 s38, s38, 0x40
	s_addc_u32 s39, s39, 0
	global_store_dwordx4 v130, v[172:175], s[46:47]
	s_nop 1
	v_permlane16_swap_b32_e32 v192, v193
	v_add_f32_e32 v192, v192, v193
	v_mov_b32_e32 v193, v192
	s_nop 1
	v_permlane32_swap_b32_e32 v192, v193
	v_add_f32_e32 v192, v192, v193
	s_mov_b64 s[74:75], exec
	s_and_b64 exec, exec, s[68:69]
	global_atomic_add_f32 v132, v192, s[38:39]
	s_mov_b64 exec, s[74:75]
	s_add_u32 s74, s48, 0xb00800
	s_addc_u32 s75, s41, 0
	global_store_dwordx4 v133, v[102:105], s[74:75]
	global_store_dwordx4 v133, v[98:101], s[74:75] offset:16
	v_mul_f32_e32 v184, v95, v95
	v_mul_f32_e32 v185, v97, v97
	v_mul_f32_e32 v186, v91, v91
	v_mul_f32_e32 v187, v93, v93
	v_fmac_f32_e32 v184, v94, v94
	v_fmac_f32_e32 v185, v96, v96
	v_fmac_f32_e32 v186, v90, v90
	v_fmac_f32_e32 v187, v92, v92
	v_pk_mul_f32 v[156:157], v[94:95], v[134:135]
	v_pk_mul_f32 v[158:159], v[96:97], v[136:137]
	v_pk_mul_f32 v[160:161], v[90:91], v[152:153]
	v_pk_mul_f32 v[162:163], v[92:93], v[154:155]
	v_add_f32_e32 v184, v184, v185
	v_add_f32_e32 v184, v186, v184
	v_add_f32_e32 v192, v187, v184
	v_cvt_pk_bf16_f32 v172, v156, v157
	v_cvt_pk_bf16_f32 v173, v158, v159
	v_cvt_pk_bf16_f32 v174, v160, v161
	v_cvt_pk_bf16_f32 v175, v162, v163
	v_mov_b32_e32 v193, v192
	s_add_u32 s46, s46, 0x1000
	s_addc_u32 s47, s47, 0
	s_add_u32 s38, s38, 0x40
	s_addc_u32 s39, s39, 0
	global_store_dwordx4 v130, v[172:175], s[46:47]
	s_nop 1
	v_permlane16_swap_b32_e32 v192, v193
	v_add_f32_e32 v192, v192, v193
	v_mov_b32_e32 v193, v192
	s_nop 1
	v_permlane32_swap_b32_e32 v192, v193
	v_add_f32_e32 v192, v192, v193
	s_mov_b64 s[74:75], exec
	s_and_b64 exec, exec, s[68:69]
	global_atomic_add_f32 v132, v192, s[38:39]
	s_mov_b64 exec, s[74:75]
	s_add_u32 s74, s48, 0xb01000
	s_addc_u32 s75, s41, 0
	global_store_dwordx4 v133, v[86:89], s[74:75]
	global_store_dwordx4 v133, v[82:85], s[74:75] offset:16
	v_mul_f32_e32 v184, v79, v79
	v_mul_f32_e32 v185, v81, v81
	v_mul_f32_e32 v186, v75, v75
	v_mul_f32_e32 v187, v77, v77
	v_fmac_f32_e32 v184, v78, v78
	v_fmac_f32_e32 v185, v80, v80
	v_fmac_f32_e32 v186, v74, v74
	v_fmac_f32_e32 v187, v76, v76
	v_pk_mul_f32 v[156:157], v[78:79], v[134:135]
	v_pk_mul_f32 v[158:159], v[80:81], v[136:137]
	v_pk_mul_f32 v[160:161], v[74:75], v[152:153]
	v_pk_mul_f32 v[162:163], v[76:77], v[154:155]
	v_add_f32_e32 v184, v184, v185
	v_add_f32_e32 v184, v186, v184
	v_add_f32_e32 v192, v187, v184
	v_cvt_pk_bf16_f32 v172, v156, v157
	v_cvt_pk_bf16_f32 v173, v158, v159
	v_cvt_pk_bf16_f32 v174, v160, v161
	v_cvt_pk_bf16_f32 v175, v162, v163
	v_mov_b32_e32 v193, v192
	s_add_u32 s46, s46, 0x1000
	s_addc_u32 s47, s47, 0
	s_add_u32 s38, s38, 0x40
	s_addc_u32 s39, s39, 0
	global_store_dwordx4 v130, v[172:175], s[46:47]
	s_nop 1
	v_permlane16_swap_b32_e32 v192, v193
	v_add_f32_e32 v192, v192, v193
	v_mov_b32_e32 v193, v192
	s_nop 1
	v_permlane32_swap_b32_e32 v192, v193
	v_add_f32_e32 v192, v192, v193
	s_mov_b64 s[74:75], exec
	s_and_b64 exec, exec, s[68:69]
	global_atomic_add_f32 v132, v192, s[38:39]
	s_mov_b64 exec, s[74:75]
	s_add_u32 s74, s48, 0xb01800
	s_addc_u32 s75, s41, 0
	global_store_dwordx4 v133, v[70:73], s[74:75]
	global_store_dwordx4 v133, v[66:69], s[74:75] offset:16
	v_mul_f32_e32 v184, v63, v63
	v_mul_f32_e32 v185, v65, v65
	v_mul_f32_e32 v186, v59, v59
	v_mul_f32_e32 v187, v61, v61
	v_fmac_f32_e32 v184, v62, v62
	v_fmac_f32_e32 v185, v64, v64
	v_fmac_f32_e32 v186, v58, v58
	v_fmac_f32_e32 v187, v60, v60
	v_pk_mul_f32 v[156:157], v[62:63], v[134:135]
	v_pk_mul_f32 v[158:159], v[64:65], v[136:137]
	v_pk_mul_f32 v[160:161], v[58:59], v[152:153]
	v_pk_mul_f32 v[162:163], v[60:61], v[154:155]
	v_add_f32_e32 v184, v184, v185
	v_add_f32_e32 v184, v186, v184
	v_add_f32_e32 v192, v187, v184
	v_cvt_pk_bf16_f32 v172, v156, v157
	v_cvt_pk_bf16_f32 v173, v158, v159
	v_cvt_pk_bf16_f32 v174, v160, v161
	v_cvt_pk_bf16_f32 v175, v162, v163
	v_mov_b32_e32 v193, v192
	s_add_u32 s46, s46, 0x5000
	s_addc_u32 s47, s47, 0
	s_add_u32 s38, s38, 0x140
	s_addc_u32 s39, s39, 0
	global_store_dwordx4 v130, v[172:175], s[46:47]
	s_nop 1
	v_permlane16_swap_b32_e32 v192, v193
	v_add_f32_e32 v192, v192, v193
	v_mov_b32_e32 v193, v192
	s_nop 1
	v_permlane32_swap_b32_e32 v192, v193
	v_add_f32_e32 v192, v192, v193
	s_mov_b64 s[74:75], exec
	s_and_b64 exec, exec, s[68:69]
	global_atomic_add_f32 v132, v192, s[38:39]
	s_mov_b64 exec, s[74:75]
	s_add_u32 s74, s48, 0xb04000
	s_addc_u32 s75, s41, 0
	global_store_dwordx4 v133, v[54:57], s[74:75]
	global_store_dwordx4 v133, v[50:53], s[74:75] offset:16
	v_mul_f32_e32 v184, v47, v47
	v_mul_f32_e32 v185, v49, v49
	v_mul_f32_e32 v186, v43, v43
	v_mul_f32_e32 v187, v45, v45
	v_fmac_f32_e32 v184, v46, v46
	v_fmac_f32_e32 v185, v48, v48
	v_fmac_f32_e32 v186, v42, v42
	v_fmac_f32_e32 v187, v44, v44
	v_pk_mul_f32 v[156:157], v[46:47], v[134:135]
	v_pk_mul_f32 v[158:159], v[48:49], v[136:137]
	v_pk_mul_f32 v[160:161], v[42:43], v[152:153]
	v_pk_mul_f32 v[162:163], v[44:45], v[154:155]
	v_add_f32_e32 v184, v184, v185
	v_add_f32_e32 v184, v186, v184
	v_add_f32_e32 v192, v187, v184
	v_cvt_pk_bf16_f32 v172, v156, v157
	v_cvt_pk_bf16_f32 v173, v158, v159
	v_cvt_pk_bf16_f32 v174, v160, v161
	v_cvt_pk_bf16_f32 v175, v162, v163
	v_mov_b32_e32 v193, v192
	s_add_u32 s46, s46, 0x1000
	s_addc_u32 s47, s47, 0
	s_add_u32 s38, s38, 0x40
	s_addc_u32 s39, s39, 0
	global_store_dwordx4 v130, v[172:175], s[46:47]
	s_nop 1
	v_permlane16_swap_b32_e32 v192, v193
	v_add_f32_e32 v192, v192, v193
	v_mov_b32_e32 v193, v192
	s_nop 1
	v_permlane32_swap_b32_e32 v192, v193
	v_add_f32_e32 v192, v192, v193
	s_mov_b64 s[74:75], exec
	s_and_b64 exec, exec, s[68:69]
	global_atomic_add_f32 v132, v192, s[38:39]
	s_mov_b64 exec, s[74:75]
	s_add_u32 s74, s48, 0xb04800
	s_addc_u32 s75, s41, 0
	global_store_dwordx4 v133, v[38:41], s[74:75]
	global_store_dwordx4 v133, v[34:37], s[74:75] offset:16
	v_mul_f32_e32 v184, v31, v31
	v_mul_f32_e32 v185, v33, v33
	v_mul_f32_e32 v186, v27, v27
	v_mul_f32_e32 v187, v29, v29
	v_fmac_f32_e32 v184, v30, v30
	v_fmac_f32_e32 v185, v32, v32
	v_fmac_f32_e32 v186, v26, v26
	v_fmac_f32_e32 v187, v28, v28
	v_pk_mul_f32 v[156:157], v[30:31], v[134:135]
	v_pk_mul_f32 v[158:159], v[32:33], v[136:137]
	v_pk_mul_f32 v[160:161], v[26:27], v[152:153]
	v_pk_mul_f32 v[162:163], v[28:29], v[154:155]
	v_add_f32_e32 v184, v184, v185
	v_add_f32_e32 v184, v186, v184
	v_add_f32_e32 v192, v187, v184
	v_cvt_pk_bf16_f32 v172, v156, v157
	v_cvt_pk_bf16_f32 v173, v158, v159
	v_cvt_pk_bf16_f32 v174, v160, v161
	v_cvt_pk_bf16_f32 v175, v162, v163
	v_mov_b32_e32 v193, v192
	s_add_u32 s46, s46, 0x1000
	s_addc_u32 s47, s47, 0
	s_add_u32 s38, s38, 0x40
	s_addc_u32 s39, s39, 0
	global_store_dwordx4 v130, v[172:175], s[46:47]
	s_nop 1
	v_permlane16_swap_b32_e32 v192, v193
	v_add_f32_e32 v192, v192, v193
	v_mov_b32_e32 v193, v192
	s_nop 1
	v_permlane32_swap_b32_e32 v192, v193
	v_add_f32_e32 v192, v192, v193
	s_mov_b64 s[74:75], exec
	s_and_b64 exec, exec, s[68:69]
	global_atomic_add_f32 v132, v192, s[38:39]
	s_mov_b64 exec, s[74:75]
	s_add_u32 s74, s48, 0xb05000
	s_addc_u32 s75, s41, 0
	global_store_dwordx4 v133, v[22:25], s[74:75]
	global_store_dwordx4 v133, v[18:21], s[74:75] offset:16
	v_mul_f32_e32 v184, v15, v15
	v_mul_f32_e32 v185, v17, v17
	v_mul_f32_e32 v186, v11, v11
	v_mul_f32_e32 v187, v13, v13
	v_fmac_f32_e32 v184, v14, v14
	v_fmac_f32_e32 v185, v16, v16
	v_fmac_f32_e32 v186, v10, v10
	v_fmac_f32_e32 v187, v12, v12
	v_pk_mul_f32 v[156:157], v[14:15], v[134:135]
	v_pk_mul_f32 v[158:159], v[16:17], v[136:137]
	v_pk_mul_f32 v[160:161], v[10:11], v[152:153]
	v_pk_mul_f32 v[162:163], v[12:13], v[154:155]
	v_add_f32_e32 v184, v184, v185
	v_add_f32_e32 v184, v186, v184
	v_add_f32_e32 v192, v187, v184
	v_cvt_pk_bf16_f32 v172, v156, v157
	v_cvt_pk_bf16_f32 v173, v158, v159
	v_cvt_pk_bf16_f32 v174, v160, v161
	v_cvt_pk_bf16_f32 v175, v162, v163
	v_mov_b32_e32 v193, v192
	s_add_u32 s46, s46, 0x1000
	s_addc_u32 s47, s47, 0
	s_add_u32 s38, s38, 0x40
	s_addc_u32 s39, s39, 0
	global_store_dwordx4 v130, v[172:175], s[46:47]
	s_nop 1
	v_permlane16_swap_b32_e32 v192, v193
	v_add_f32_e32 v192, v192, v193
	v_mov_b32_e32 v193, v192
	s_nop 1
	v_permlane32_swap_b32_e32 v192, v193
	v_add_f32_e32 v192, v192, v193
	s_mov_b64 s[74:75], exec
	s_and_b64 exec, exec, s[68:69]
	global_atomic_add_f32 v132, v192, s[38:39]
	s_mov_b64 exec, s[74:75]
	s_add_u32 s74, s48, 0xb05800
	s_addc_u32 s75, s41, 0
	global_store_dwordx4 v133, v[6:9], s[74:75]
	global_store_dwordx4 v133, v[2:5], s[74:75] offset:16
	s_branch .LBB0_1251
.Lepi_lat_kv_alr:
	v_readlane_b32 s68, v255, 36
	v_readlane_b32 s69, v255, 37
	s_lshl_b32 s78, s26, 2
	s_nop 1
	s_add_u32 s68, s68, s78
	s_addc_u32 s69, s69, 0
	v_lshlrev_b32_e32 v131, 2, v176
	global_load_dwordx4 v[134:137], v131, s[68:69] offset:0
	global_load_dwordx4 v[152:155], v131, s[68:69] offset:16
	s_mul_i32 s8, s9, 256
	s_lshl_b32 s78, s26, 1
	s_add_i32 s8, s8, s78
	s_add_u32 s46, s36, s8
	s_addc_u32 s47, s37, 0
	s_add_u32 s46, s46, 0x1e600000
	s_addc_u32 s47, s47, 0
	s_lshl_b32 s8, s9, 2
	s_add_u32 s38, s36, s8
	s_addc_u32 s39, s37, 0
	s_add_u32 s38, s38, 0x1140000
	s_addc_u32 s39, s39, 0
	v_mul_u32_u24_e32 v130, 256, v1
	v_lshl_add_u32 v130, v176, 1, v130
	v_lshlrev_b32_e32 v132, 2, v1
	v_cmp_eq_u32_e64 s[68:69], 0, v176
	s_mul_i32 s8, s9, 64
	s_add_u32 s48, s36, s8
	s_addc_u32 s41, s37, 0
	v_mul_u32_u24_e32 v133, 64, v1
	v_lshl_add_u32 v133, v176, 2, v133
	s_waitcnt vmcnt(0)
	v_mul_f32_e32 v184, v127, v127
	v_mul_f32_e32 v185, v129, v129
	v_mul_f32_e32 v186, v123, v123
	v_mul_f32_e32 v187, v125, v125
	v_fmac_f32_e32 v184, v126, v126
	v_fmac_f32_e32 v185, v128, v128
	v_fmac_f32_e32 v186, v122, v122
	v_fmac_f32_e32 v187, v124, v124
	v_pk_mul_f32 v[156:157], v[126:127], v[134:135]
	v_pk_mul_f32 v[158:159], v[128:129], v[136:137]
	v_pk_mul_f32 v[160:161], v[122:123], v[152:153]
	v_pk_mul_f32 v[162:163], v[124:125], v[154:155]
	v_add_f32_e32 v184, v184, v185
	v_add_f32_e32 v184, v186, v184
	v_add_f32_e32 v192, v187, v184
	v_cvt_pk_bf16_f32 v172, v156, v157
	v_cvt_pk_bf16_f32 v173, v158, v159
	v_cvt_pk_bf16_f32 v174, v160, v161
	v_cvt_pk_bf16_f32 v175, v162, v163
	v_mov_b32_e32 v193, v192
	global_store_dwordx4 v130, v[172:175], s[46:47]
	s_nop 1
	v_permlane16_swap_b32_e32 v192, v193
	v_add_f32_e32 v192, v192, v193
	v_mov_b32_e32 v193, v192
	s_nop 1
	v_permlane32_swap_b32_e32 v192, v193
	v_add_f32_e32 v192, v192, v193
	s_mov_b64 s[74:75], exec
	s_and_b64 exec, exec, s[68:69]
	global_atomic_add_f32 v132, v192, s[38:39]
	s_mov_b64 exec, s[74:75]
	s_add_u32 s74, s48, 0xf00000
	s_addc_u32 s75, s41, 0
	v_cmp_gt_u32_e32 vcc, 16, v176
	s_and_saveexec_b64 s[78:79], vcc
	global_store_dwordx4 v133, v[118:121], s[74:75]
	global_store_dwordx4 v133, v[114:117], s[74:75] offset:16
	s_mov_b64 exec, s[78:79]
	v_mul_f32_e32 v184, v111, v111
	v_mul_f32_e32 v185, v113, v113
	v_mul_f32_e32 v186, v107, v107
	v_mul_f32_e32 v187, v109, v109
	v_fmac_f32_e32 v184, v110, v110
	v_fmac_f32_e32 v185, v112, v112
	v_fmac_f32_e32 v186, v106, v106
	v_fmac_f32_e32 v187, v108, v108
	v_pk_mul_f32 v[156:157], v[110:111], v[134:135]
	v_pk_mul_f32 v[158:159], v[112:113], v[136:137]
	v_pk_mul_f32 v[160:161], v[106:107], v[152:153]
	v_pk_mul_f32 v[162:163], v[108:109], v[154:155]
	v_add_f32_e32 v184, v184, v185
	v_add_f32_e32 v184, v186, v184
	v_add_f32_e32 v192, v187, v184
	v_cvt_pk_bf16_f32 v172, v156, v157
	v_cvt_pk_bf16_f32 v173, v158, v159
	v_cvt_pk_bf16_f32 v174, v160, v161
	v_cvt_pk_bf16_f32 v175, v162, v163
	v_mov_b32_e32 v193, v192
	s_add_u32 s46, s46, 0x1000
	s_addc_u32 s47, s47, 0
	s_add_u32 s38, s38, 0x40
	s_addc_u32 s39, s39, 0
	global_store_dwordx4 v130, v[172:175], s[46:47]
	s_nop 1
	v_permlane16_swap_b32_e32 v192, v193
	v_add_f32_e32 v192, v192, v193
	v_mov_b32_e32 v193, v192
	s_nop 1
	v_permlane32_swap_b32_e32 v192, v193
	v_add_f32_e32 v192, v192, v193
	s_mov_b64 s[74:75], exec
	s_and_b64 exec, exec, s[68:69]
	global_atomic_add_f32 v132, v192, s[38:39]
	s_mov_b64 exec, s[74:75]
	s_add_u32 s74, s48, 0xf00400
	s_addc_u32 s75, s41, 0
	v_cmp_gt_u32_e32 vcc, 16, v176
	s_and_saveexec_b64 s[78:79], vcc
	global_store_dwordx4 v133, v[102:105], s[74:75]
	global_store_dwordx4 v133, v[98:101], s[74:75] offset:16
	s_mov_b64 exec, s[78:79]
	v_mul_f32_e32 v184, v95, v95
	v_mul_f32_e32 v185, v97, v97
	v_mul_f32_e32 v186, v91, v91
	v_mul_f32_e32 v187, v93, v93
	v_fmac_f32_e32 v184, v94, v94
	v_fmac_f32_e32 v185, v96, v96
	v_fmac_f32_e32 v186, v90, v90
	v_fmac_f32_e32 v187, v92, v92
	v_pk_mul_f32 v[156:157], v[94:95], v[134:135]
	v_pk_mul_f32 v[158:159], v[96:97], v[136:137]
	v_pk_mul_f32 v[160:161], v[90:91], v[152:153]
	v_pk_mul_f32 v[162:163], v[92:93], v[154:155]
	v_add_f32_e32 v184, v184, v185
	v_add_f32_e32 v184, v186, v184
	v_add_f32_e32 v192, v187, v184
	v_cvt_pk_bf16_f32 v172, v156, v157
	v_cvt_pk_bf16_f32 v173, v158, v159
	v_cvt_pk_bf16_f32 v174, v160, v161
	v_cvt_pk_bf16_f32 v175, v162, v163
	v_mov_b32_e32 v193, v192
	s_add_u32 s46, s46, 0x1000
	s_addc_u32 s47, s47, 0
	s_add_u32 s38, s38, 0x40
	s_addc_u32 s39, s39, 0
	global_store_dwordx4 v130, v[172:175], s[46:47]
	s_nop 1
	v_permlane16_swap_b32_e32 v192, v193
	v_add_f32_e32 v192, v192, v193
	v_mov_b32_e32 v193, v192
	s_nop 1
	v_permlane32_swap_b32_e32 v192, v193
	v_add_f32_e32 v192, v192, v193
	s_mov_b64 s[74:75], exec
	s_and_b64 exec, exec, s[68:69]
	global_atomic_add_f32 v132, v192, s[38:39]
	s_mov_b64 exec, s[74:75]
	s_add_u32 s74, s48, 0xf00800
	s_addc_u32 s75, s41, 0
	v_cmp_gt_u32_e32 vcc, 16, v176
	s_and_saveexec_b64 s[78:79], vcc
	global_store_dwordx4 v133, v[86:89], s[74:75]
	global_store_dwordx4 v133, v[82:85], s[74:75] offset:16
	s_mov_b64 exec, s[78:79]
	v_mul_f32_e32 v184, v79, v79
	v_mul_f32_e32 v185, v81, v81
	v_mul_f32_e32 v186, v75, v75
	v_mul_f32_e32 v187, v77, v77
	v_fmac_f32_e32 v184, v78, v78
	v_fmac_f32_e32 v185, v80, v80
	v_fmac_f32_e32 v186, v74, v74
	v_fmac_f32_e32 v187, v76, v76
	v_pk_mul_f32 v[156:157], v[78:79], v[134:135]
	v_pk_mul_f32 v[158:159], v[80:81], v[136:137]
	v_pk_mul_f32 v[160:161], v[74:75], v[152:153]
	v_pk_mul_f32 v[162:163], v[76:77], v[154:155]
	v_add_f32_e32 v184, v184, v185
	v_add_f32_e32 v184, v186, v184
	v_add_f32_e32 v192, v187, v184
	v_cvt_pk_bf16_f32 v172, v156, v157
	v_cvt_pk_bf16_f32 v173, v158, v159
	v_cvt_pk_bf16_f32 v174, v160, v161
	v_cvt_pk_bf16_f32 v175, v162, v163
	v_mov_b32_e32 v193, v192
	s_add_u32 s46, s46, 0x1000
	s_addc_u32 s47, s47, 0
	s_add_u32 s38, s38, 0x40
	s_addc_u32 s39, s39, 0
	global_store_dwordx4 v130, v[172:175], s[46:47]
	s_nop 1
	v_permlane16_swap_b32_e32 v192, v193
	v_add_f32_e32 v192, v192, v193
	v_mov_b32_e32 v193, v192
	s_nop 1
	v_permlane32_swap_b32_e32 v192, v193
	v_add_f32_e32 v192, v192, v193
	s_mov_b64 s[74:75], exec
	s_and_b64 exec, exec, s[68:69]
	global_atomic_add_f32 v132, v192, s[38:39]
	s_mov_b64 exec, s[74:75]
	s_add_u32 s74, s48, 0xf00c00
	s_addc_u32 s75, s41, 0
	v_cmp_gt_u32_e32 vcc, 16, v176
	s_and_saveexec_b64 s[78:79], vcc
	global_store_dwordx4 v133, v[70:73], s[74:75]
	global_store_dwordx4 v133, v[66:69], s[74:75] offset:16
	s_mov_b64 exec, s[78:79]
	v_mul_f32_e32 v184, v63, v63
	v_mul_f32_e32 v185, v65, v65
	v_mul_f32_e32 v186, v59, v59
	v_mul_f32_e32 v187, v61, v61
	v_fmac_f32_e32 v184, v62, v62
	v_fmac_f32_e32 v185, v64, v64
	v_fmac_f32_e32 v186, v58, v58
	v_fmac_f32_e32 v187, v60, v60
	v_pk_mul_f32 v[156:157], v[62:63], v[134:135]
	v_pk_mul_f32 v[158:159], v[64:65], v[136:137]
	v_pk_mul_f32 v[160:161], v[58:59], v[152:153]
	v_pk_mul_f32 v[162:163], v[60:61], v[154:155]
	v_add_f32_e32 v184, v184, v185
	v_add_f32_e32 v184, v186, v184
	v_add_f32_e32 v192, v187, v184
	v_cvt_pk_bf16_f32 v172, v156, v157
	v_cvt_pk_bf16_f32 v173, v158, v159
	v_cvt_pk_bf16_f32 v174, v160, v161
	v_cvt_pk_bf16_f32 v175, v162, v163
	v_mov_b32_e32 v193, v192
	s_add_u32 s46, s46, 0x5000
	s_addc_u32 s47, s47, 0
	s_add_u32 s38, s38, 0x140
	s_addc_u32 s39, s39, 0
	global_store_dwordx4 v130, v[172:175], s[46:47]
	s_nop 1
	v_permlane16_swap_b32_e32 v192, v193
	v_add_f32_e32 v192, v192, v193
	v_mov_b32_e32 v193, v192
	s_nop 1
	v_permlane32_swap_b32_e32 v192, v193
	v_add_f32_e32 v192, v192, v193
	s_mov_b64 s[74:75], exec
	s_and_b64 exec, exec, s[68:69]
	global_atomic_add_f32 v132, v192, s[38:39]
	s_mov_b64 exec, s[74:75]
	s_add_u32 s74, s48, 0xf02000
	s_addc_u32 s75, s41, 0
	v_cmp_gt_u32_e32 vcc, 16, v176
	s_and_saveexec_b64 s[78:79], vcc
	global_store_dwordx4 v133, v[54:57], s[74:75]
	global_store_dwordx4 v133, v[50:53], s[74:75] offset:16
	s_mov_b64 exec, s[78:79]
	v_mul_f32_e32 v184, v47, v47
	v_mul_f32_e32 v185, v49, v49
	v_mul_f32_e32 v186, v43, v43
	v_mul_f32_e32 v187, v45, v45
	v_fmac_f32_e32 v184, v46, v46
	v_fmac_f32_e32 v185, v48, v48
	v_fmac_f32_e32 v186, v42, v42
	v_fmac_f32_e32 v187, v44, v44
	v_pk_mul_f32 v[156:157], v[46:47], v[134:135]
	v_pk_mul_f32 v[158:159], v[48:49], v[136:137]
	v_pk_mul_f32 v[160:161], v[42:43], v[152:153]
	v_pk_mul_f32 v[162:163], v[44:45], v[154:155]
	v_add_f32_e32 v184, v184, v185
	v_add_f32_e32 v184, v186, v184
	v_add_f32_e32 v192, v187, v184
	v_cvt_pk_bf16_f32 v172, v156, v157
	v_cvt_pk_bf16_f32 v173, v158, v159
	v_cvt_pk_bf16_f32 v174, v160, v161
	v_cvt_pk_bf16_f32 v175, v162, v163
	v_mov_b32_e32 v193, v192
	s_add_u32 s46, s46, 0x1000
	s_addc_u32 s47, s47, 0
	s_add_u32 s38, s38, 0x40
	s_addc_u32 s39, s39, 0
	global_store_dwordx4 v130, v[172:175], s[46:47]
	s_nop 1
	v_permlane16_swap_b32_e32 v192, v193
	v_add_f32_e32 v192, v192, v193
	v_mov_b32_e32 v193, v192
	s_nop 1
	v_permlane32_swap_b32_e32 v192, v193
	v_add_f32_e32 v192, v192, v193
	s_mov_b64 s[74:75], exec
	s_and_b64 exec, exec, s[68:69]
	global_atomic_add_f32 v132, v192, s[38:39]
	s_mov_b64 exec, s[74:75]
	s_add_u32 s74, s48, 0xf02400
	s_addc_u32 s75, s41, 0
	v_cmp_gt_u32_e32 vcc, 16, v176
	s_and_saveexec_b64 s[78:79], vcc
	global_store_dwordx4 v133, v[38:41], s[74:75]
	global_store_dwordx4 v133, v[34:37], s[74:75] offset:16
	s_mov_b64 exec, s[78:79]
	v_mul_f32_e32 v184, v31, v31
	v_mul_f32_e32 v185, v33, v33
	v_mul_f32_e32 v186, v27, v27
	v_mul_f32_e32 v187, v29, v29
	v_fmac_f32_e32 v184, v30, v30
	v_fmac_f32_e32 v185, v32, v32
	v_fmac_f32_e32 v186, v26, v26
	v_fmac_f32_e32 v187, v28, v28
	v_pk_mul_f32 v[156:157], v[30:31], v[134:135]
	v_pk_mul_f32 v[158:159], v[32:33], v[136:137]
	v_pk_mul_f32 v[160:161], v[26:27], v[152:153]
	v_pk_mul_f32 v[162:163], v[28:29], v[154:155]
	v_add_f32_e32 v184, v184, v185
	v_add_f32_e32 v184, v186, v184
	v_add_f32_e32 v192, v187, v184
	v_cvt_pk_bf16_f32 v172, v156, v157
	v_cvt_pk_bf16_f32 v173, v158, v159
	v_cvt_pk_bf16_f32 v174, v160, v161
	v_cvt_pk_bf16_f32 v175, v162, v163
	v_mov_b32_e32 v193, v192
	s_add_u32 s46, s46, 0x1000
	s_addc_u32 s47, s47, 0
	s_add_u32 s38, s38, 0x40
	s_addc_u32 s39, s39, 0
	global_store_dwordx4 v130, v[172:175], s[46:47]
	s_nop 1
	v_permlane16_swap_b32_e32 v192, v193
	v_add_f32_e32 v192, v192, v193
	v_mov_b32_e32 v193, v192
	s_nop 1
	v_permlane32_swap_b32_e32 v192, v193
	v_add_f32_e32 v192, v192, v193
	s_mov_b64 s[74:75], exec
	s_and_b64 exec, exec, s[68:69]
	global_atomic_add_f32 v132, v192, s[38:39]
	s_mov_b64 exec, s[74:75]
	s_add_u32 s74, s48, 0xf02800
	s_addc_u32 s75, s41, 0
	v_cmp_gt_u32_e32 vcc, 16, v176
	s_and_saveexec_b64 s[78:79], vcc
	global_store_dwordx4 v133, v[22:25], s[74:75]
	global_store_dwordx4 v133, v[18:21], s[74:75] offset:16
	s_mov_b64 exec, s[78:79]
	v_mul_f32_e32 v184, v15, v15
	v_mul_f32_e32 v185, v17, v17
	v_mul_f32_e32 v186, v11, v11
	v_mul_f32_e32 v187, v13, v13
	v_fmac_f32_e32 v184, v14, v14
	v_fmac_f32_e32 v185, v16, v16
	v_fmac_f32_e32 v186, v10, v10
	v_fmac_f32_e32 v187, v12, v12
	v_pk_mul_f32 v[156:157], v[14:15], v[134:135]
	v_pk_mul_f32 v[158:159], v[16:17], v[136:137]
	v_pk_mul_f32 v[160:161], v[10:11], v[152:153]
	v_pk_mul_f32 v[162:163], v[12:13], v[154:155]
	v_add_f32_e32 v184, v184, v185
	v_add_f32_e32 v184, v186, v184
	v_add_f32_e32 v192, v187, v184
	v_cvt_pk_bf16_f32 v172, v156, v157
	v_cvt_pk_bf16_f32 v173, v158, v159
	v_cvt_pk_bf16_f32 v174, v160, v161
	v_cvt_pk_bf16_f32 v175, v162, v163
	v_mov_b32_e32 v193, v192
	s_add_u32 s46, s46, 0x1000
	s_addc_u32 s47, s47, 0
	s_add_u32 s38, s38, 0x40
	s_addc_u32 s39, s39, 0
	global_store_dwordx4 v130, v[172:175], s[46:47]
	s_nop 1
	v_permlane16_swap_b32_e32 v192, v193
	v_add_f32_e32 v192, v192, v193
	v_mov_b32_e32 v193, v192
	s_nop 1
	v_permlane32_swap_b32_e32 v192, v193
	v_add_f32_e32 v192, v192, v193
	s_mov_b64 s[74:75], exec
	s_and_b64 exec, exec, s[68:69]
	global_atomic_add_f32 v132, v192, s[38:39]
	s_mov_b64 exec, s[74:75]
	s_add_u32 s74, s48, 0xf02c00
	s_addc_u32 s75, s41, 0
	v_cmp_gt_u32_e32 vcc, 16, v176
	s_and_saveexec_b64 s[78:79], vcc
	global_store_dwordx4 v133, v[6:9], s[74:75]
	global_store_dwordx4 v133, v[2:5], s[74:75] offset:16
	s_mov_b64 exec, s[78:79]
	s_branch .LBB0_1251
.Lepi_lat_cq:
	v_readlane_b32 s68, v255, 34
	v_readlane_b32 s69, v255, 35
	s_lshl_b32 s78, s26, 2
	s_nop 1
	s_add_u32 s68, s68, s78
	s_addc_u32 s69, s69, 0
	v_lshlrev_b32_e32 v131, 2, v176
	global_load_dwordx4 v[134:137], v131, s[68:69] offset:0
	global_load_dwordx4 v[152:155], v131, s[68:69] offset:16
	global_load_dwordx4 v[156:159], v131, s[68:69] offset:512
	global_load_dwordx4 v[160:163], v131, s[68:69] offset:528
	s_mul_i32 s8, s9, 512
	s_lshl_b32 s78, s26, 1
	s_add_i32 s8, s8, s78
	s_add_u32 s46, s36, s8
	s_addc_u32 s47, s37, 0
	s_add_u32 s46, s46, 0x1d600000
	s_addc_u32 s47, s47, 0
	s_lshl_b32 s8, s9, 2
	s_add_u32 s38, s36, s8
	s_addc_u32 s39, s37, 0
	s_add_u32 s38, s38, 0x1100000
	s_addc_u32 s39, s39, 0
	v_mul_u32_u24_e32 v130, 512, v1
	v_lshl_add_u32 v130, v176, 1, v130
	v_lshlrev_b32_e32 v132, 2, v1
	v_cmp_eq_u32_e64 s[68:69], 0, v176
	s_waitcnt vmcnt(0)
	v_mul_f32_e32 v192, v127, v127
	v_mul_f32_e32 v193, v129, v129
	v_mul_f32_e32 v194, v123, v123
	v_mul_f32_e32 v195, v125, v125
	v_fmac_f32_e32 v192, v126, v126
	v_fmac_f32_e32 v193, v128, v128
	v_fmac_f32_e32 v194, v122, v122
	v_fmac_f32_e32 v195, v124, v124
	v_pk_mul_f32 v[164:165], v[126:127], v[134:135]
	v_pk_mul_f32 v[166:167], v[128:129], v[136:137]
	v_pk_mul_f32 v[168:169], v[122:123], v[152:153]
	v_pk_mul_f32 v[170:171], v[124:125], v[154:155]
	v_add_f32_e32 v192, v192, v193
	v_add_f32_e32 v192, v194, v192
	v_add_f32_e32 v200, v195, v192
	v_cvt_pk_bf16_f32 v172, v164, v165
	v_cvt_pk_bf16_f32 v173, v166, v167
	v_cvt_pk_bf16_f32 v174, v168, v169
	v_cvt_pk_bf16_f32 v175, v170, v171
	v_mov_b32_e32 v201, v200
	global_store_dwordx4 v130, v[172:175], s[46:47]
	s_nop 1
	v_permlane16_swap_b32_e32 v200, v201
	v_add_f32_e32 v200, v200, v201
	v_mov_b32_e32 v201, v200
	s_nop 1
	v_permlane32_swap_b32_e32 v200, v201
	v_add_f32_e32 v200, v200, v201
	s_mov_b64 s[74:75], exec
	s_and_b64 exec, exec, s[68:69]
	global_atomic_add_f32 v132, v200, s[38:39]
	s_mov_b64 exec, s[74:75]
	v_mul_f32_e32 v196, v119, v119
	v_mul_f32_e32 v197, v121, v121
	v_mul_f32_e32 v198, v115, v115
	v_mul_f32_e32 v199, v117, v117
	v_fmac_f32_e32 v196, v118, v118
	v_fmac_f32_e32 v197, v120, v120
	v_fmac_f32_e32 v198, v114, v114
	v_fmac_f32_e32 v199, v116, v116
	v_pk_mul_f32 v[180:181], v[118:119], v[156:157]
	v_pk_mul_f32 v[182:183], v[120:121], v[158:159]
	v_pk_mul_f32 v[184:185], v[114:115], v[160:161]
	v_pk_mul_f32 v[186:187], v[116:117], v[162:163]
	v_add_f32_e32 v196, v196, v197
	v_add_f32_e32 v196, v198, v196
	v_add_f32_e32 v202, v199, v196
	v_cvt_pk_bf16_f32 v188, v180, v181
	v_cvt_pk_bf16_f32 v189, v182, v183
	v_cvt_pk_bf16_f32 v190, v184, v185
	v_cvt_pk_bf16_f32 v191, v186, v187
	v_mov_b32_e32 v203, v202
	global_store_dwordx4 v130, v[188:191], s[46:47] offset:256
	s_nop 1
	v_permlane16_swap_b32_e32 v202, v203
	v_add_f32_e32 v202, v202, v203
	v_mov_b32_e32 v203, v202
	s_nop 1
	v_permlane32_swap_b32_e32 v202, v203
	v_add_f32_e32 v202, v202, v203
	s_mov_b64 s[74:75], exec
	s_and_b64 exec, exec, s[68:69]
	global_atomic_add_f32 v132, v202, s[38:39]
	s_mov_b64 exec, s[74:75]
	v_mul_f32_e32 v192, v111, v111
	v_mul_f32_e32 v193, v113, v113
	v_mul_f32_e32 v194, v107, v107
	v_mul_f32_e32 v195, v109, v109
	v_fmac_f32_e32 v192, v110, v110
	v_fmac_f32_e32 v193, v112, v112
	v_fmac_f32_e32 v194, v106, v106
	v_fmac_f32_e32 v195, v108, v108
	v_pk_mul_f32 v[164:165], v[110:111], v[134:135]
	v_pk_mul_f32 v[166:167], v[112:113], v[136:137]
	v_pk_mul_f32 v[168:169], v[106:107], v[152:153]
	v_pk_mul_f32 v[170:171], v[108:109], v[154:155]
	v_add_f32_e32 v192, v192, v193
	v_add_f32_e32 v192, v194, v192
	v_add_f32_e32 v200, v195, v192
	v_cvt_pk_bf16_f32 v172, v164, v165
	v_cvt_pk_bf16_f32 v173, v166, v167
	v_cvt_pk_bf16_f32 v174, v168, v169
	v_cvt_pk_bf16_f32 v175, v170, v171
	v_mov_b32_e32 v201, v200
	s_add_u32 s46, s46, 0x2000
	s_addc_u32 s47, s47, 0
	s_add_u32 s38, s38, 0x40
	s_addc_u32 s39, s39, 0
	global_store_dwordx4 v130, v[172:175], s[46:47]
	s_nop 1
	v_permlane16_swap_b32_e32 v200, v201
	v_add_f32_e32 v200, v200, v201
	v_mov_b32_e32 v201, v200
	s_nop 1
	v_permlane32_swap_b32_e32 v200, v201
	v_add_f32_e32 v200, v200, v201
	s_mov_b64 s[74:75], exec
	s_and_b64 exec, exec, s[68:69]
	global_atomic_add_f32 v132, v200, s[38:39]
	s_mov_b64 exec, s[74:75]
	v_mul_f32_e32 v196, v103, v103
	v_mul_f32_e32 v197, v105, v105
	v_mul_f32_e32 v198, v99, v99
	v_mul_f32_e32 v199, v101, v101
	v_fmac_f32_e32 v196, v102, v102
	v_fmac_f32_e32 v197, v104, v104
	v_fmac_f32_e32 v198, v98, v98
	v_fmac_f32_e32 v199, v100, v100
	v_pk_mul_f32 v[180:181], v[102:103], v[156:157]
	v_pk_mul_f32 v[182:183], v[104:105], v[158:159]
	v_pk_mul_f32 v[184:185], v[98:99], v[160:161]
	v_pk_mul_f32 v[186:187], v[100:101], v[162:163]
	v_add_f32_e32 v196, v196, v197
	v_add_f32_e32 v196, v198, v196
	v_add_f32_e32 v202, v199, v196
	v_cvt_pk_bf16_f32 v188, v180, v181
	v_cvt_pk_bf16_f32 v189, v182, v183
	v_cvt_pk_bf16_f32 v190, v184, v185
	v_cvt_pk_bf16_f32 v191, v186, v187
	v_mov_b32_e32 v203, v202
	global_store_dwordx4 v130, v[188:191], s[46:47] offset:256
	s_nop 1
	v_permlane16_swap_b32_e32 v202, v203
	v_add_f32_e32 v202, v202, v203
	v_mov_b32_e32 v203, v202
	s_nop 1
	v_permlane32_swap_b32_e32 v202, v203
	v_add_f32_e32 v202, v202, v203
	s_mov_b64 s[74:75], exec
	s_and_b64 exec, exec, s[68:69]
	global_atomic_add_f32 v132, v202, s[38:39]
	s_mov_b64 exec, s[74:75]
	v_mul_f32_e32 v192, v95, v95
	v_mul_f32_e32 v193, v97, v97
	v_mul_f32_e32 v194, v91, v91
	v_mul_f32_e32 v195, v93, v93
	v_fmac_f32_e32 v192, v94, v94
	v_fmac_f32_e32 v193, v96, v96
	v_fmac_f32_e32 v194, v90, v90
	v_fmac_f32_e32 v195, v92, v92
	v_pk_mul_f32 v[164:165], v[94:95], v[134:135]
	v_pk_mul_f32 v[166:167], v[96:97], v[136:137]
	v_pk_mul_f32 v[168:169], v[90:91], v[152:153]
	v_pk_mul_f32 v[170:171], v[92:93], v[154:155]
	v_add_f32_e32 v192, v192, v193
	v_add_f32_e32 v192, v194, v192
	v_add_f32_e32 v200, v195, v192
	v_cvt_pk_bf16_f32 v172, v164, v165
	v_cvt_pk_bf16_f32 v173, v166, v167
	v_cvt_pk_bf16_f32 v174, v168, v169
	v_cvt_pk_bf16_f32 v175, v170, v171
	v_mov_b32_e32 v201, v200
	s_add_u32 s46, s46, 0x2000
	s_addc_u32 s47, s47, 0
	s_add_u32 s38, s38, 0x40
	s_addc_u32 s39, s39, 0
	global_store_dwordx4 v130, v[172:175], s[46:47]
	s_nop 1
	v_permlane16_swap_b32_e32 v200, v201
	v_add_f32_e32 v200, v200, v201
	v_mov_b32_e32 v201, v200
	s_nop 1
	v_permlane32_swap_b32_e32 v200, v201
	v_add_f32_e32 v200, v200, v201
	s_mov_b64 s[74:75], exec
	s_and_b64 exec, exec, s[68:69]
	global_atomic_add_f32 v132, v200, s[38:39]
	s_mov_b64 exec, s[74:75]
	v_mul_f32_e32 v196, v87, v87
	v_mul_f32_e32 v197, v89, v89
	v_mul_f32_e32 v198, v83, v83
	v_mul_f32_e32 v199, v85, v85
	v_fmac_f32_e32 v196, v86, v86
	v_fmac_f32_e32 v197, v88, v88
	v_fmac_f32_e32 v198, v82, v82
	v_fmac_f32_e32 v199, v84, v84
	v_pk_mul_f32 v[180:181], v[86:87], v[156:157]
	v_pk_mul_f32 v[182:183], v[88:89], v[158:159]
	v_pk_mul_f32 v[184:185], v[82:83], v[160:161]
	v_pk_mul_f32 v[186:187], v[84:85], v[162:163]
	v_add_f32_e32 v196, v196, v197
	v_add_f32_e32 v196, v198, v196
	v_add_f32_e32 v202, v199, v196
	v_cvt_pk_bf16_f32 v188, v180, v181
	v_cvt_pk_bf16_f32 v189, v182, v183
	v_cvt_pk_bf16_f32 v190, v184, v185
	v_cvt_pk_bf16_f32 v191, v186, v187
	v_mov_b32_e32 v203, v202
	global_store_dwordx4 v130, v[188:191], s[46:47] offset:256
	s_nop 1
	v_permlane16_swap_b32_e32 v202, v203
	v_add_f32_e32 v202, v202, v203
	v_mov_b32_e32 v203, v202
	s_nop 1
	v_permlane32_swap_b32_e32 v202, v203
	v_add_f32_e32 v202, v202, v203
	s_mov_b64 s[74:75], exec
	s_and_b64 exec, exec, s[68:69]
	global_atomic_add_f32 v132, v202, s[38:39]
	s_mov_b64 exec, s[74:75]
	v_mul_f32_e32 v192, v79, v79
	v_mul_f32_e32 v193, v81, v81
	v_mul_f32_e32 v194, v75, v75
	v_mul_f32_e32 v195, v77, v77
	v_fmac_f32_e32 v192, v78, v78
	v_fmac_f32_e32 v193, v80, v80
	v_fmac_f32_e32 v194, v74, v74
	v_fmac_f32_e32 v195, v76, v76
	v_pk_mul_f32 v[164:165], v[78:79], v[134:135]
	v_pk_mul_f32 v[166:167], v[80:81], v[136:137]
	v_pk_mul_f32 v[168:169], v[74:75], v[152:153]
	v_pk_mul_f32 v[170:171], v[76:77], v[154:155]
	v_add_f32_e32 v192, v192, v193
	v_add_f32_e32 v192, v194, v192
	v_add_f32_e32 v200, v195, v192
	v_cvt_pk_bf16_f32 v172, v164, v165
	v_cvt_pk_bf16_f32 v173, v166, v167
	v_cvt_pk_bf16_f32 v174, v168, v169
	v_cvt_pk_bf16_f32 v175, v170, v171
	v_mov_b32_e32 v201, v200
	s_add_u32 s46, s46, 0x2000
	s_addc_u32 s47, s47, 0
	s_add_u32 s38, s38, 0x40
	s_addc_u32 s39, s39, 0
	global_store_dwordx4 v130, v[172:175], s[46:47]
	s_nop 1
	v_permlane16_swap_b32_e32 v200, v201
	v_add_f32_e32 v200, v200, v201
	v_mov_b32_e32 v201, v200
	s_nop 1
	v_permlane32_swap_b32_e32 v200, v201
	v_add_f32_e32 v200, v200, v201
	s_mov_b64 s[74:75], exec
	s_and_b64 exec, exec, s[68:69]
	global_atomic_add_f32 v132, v200, s[38:39]
	s_mov_b64 exec, s[74:75]
	v_mul_f32_e32 v196, v71, v71
	v_mul_f32_e32 v197, v73, v73
	v_mul_f32_e32 v198, v67, v67
	v_mul_f32_e32 v199, v69, v69
	v_fmac_f32_e32 v196, v70, v70
	v_fmac_f32_e32 v197, v72, v72
	v_fmac_f32_e32 v198, v66, v66
	v_fmac_f32_e32 v199, v68, v68
	v_pk_mul_f32 v[180:181], v[70:71], v[156:157]
	v_pk_mul_f32 v[182:183], v[72:73], v[158:159]
	v_pk_mul_f32 v[184:185], v[66:67], v[160:161]
	v_pk_mul_f32 v[186:187], v[68:69], v[162:163]
	v_add_f32_e32 v196, v196, v197
	v_add_f32_e32 v196, v198, v196
	v_add_f32_e32 v202, v199, v196
	v_cvt_pk_bf16_f32 v188, v180, v181
	v_cvt_pk_bf16_f32 v189, v182, v183
	v_cvt_pk_bf16_f32 v190, v184, v185
	v_cvt_pk_bf16_f32 v191, v186, v187
	v_mov_b32_e32 v203, v202
	global_store_dwordx4 v130, v[188:191], s[46:47] offset:256
	s_nop 1
	v_permlane16_swap_b32_e32 v202, v203
	v_add_f32_e32 v202, v202, v203
	v_mov_b32_e32 v203, v202
	s_nop 1
	v_permlane32_swap_b32_e32 v202, v203
	v_add_f32_e32 v202, v202, v203
	s_mov_b64 s[74:75], exec
	s_and_b64 exec, exec, s[68:69]
	global_atomic_add_f32 v132, v202, s[38:39]
	s_mov_b64 exec, s[74:75]
	v_mul_f32_e32 v192, v63, v63
	v_mul_f32_e32 v193, v65, v65
	v_mul_f32_e32 v194, v59, v59
	v_mul_f32_e32 v195, v61, v61
	v_fmac_f32_e32 v192, v62, v62
	v_fmac_f32_e32 v193, v64, v64
	v_fmac_f32_e32 v194, v58, v58
	v_fmac_f32_e32 v195, v60, v60
	v_pk_mul_f32 v[164:165], v[62:63], v[134:135]
	v_pk_mul_f32 v[166:167], v[64:65], v[136:137]
	v_pk_mul_f32 v[168:169], v[58:59], v[152:153]
	v_pk_mul_f32 v[170:171], v[60:61], v[154:155]
	v_add_f32_e32 v192, v192, v193
	v_add_f32_e32 v192, v194, v192
	v_add_f32_e32 v200, v195, v192
	v_cvt_pk_bf16_f32 v172, v164, v165
	v_cvt_pk_bf16_f32 v173, v166, v167
	v_cvt_pk_bf16_f32 v174, v168, v169
	v_cvt_pk_bf16_f32 v175, v170, v171
	v_mov_b32_e32 v201, v200
	s_add_u32 s46, s46, 0xa000
	s_addc_u32 s47, s47, 0
	s_add_u32 s38, s38, 0x140
	s_addc_u32 s39, s39, 0
	global_store_dwordx4 v130, v[172:175], s[46:47]
	s_nop 1
	v_permlane16_swap_b32_e32 v200, v201
	v_add_f32_e32 v200, v200, v201
	v_mov_b32_e32 v201, v200
	s_nop 1
	v_permlane32_swap_b32_e32 v200, v201
	v_add_f32_e32 v200, v200, v201
	s_mov_b64 s[74:75], exec
	s_and_b64 exec, exec, s[68:69]
	global_atomic_add_f32 v132, v200, s[38:39]
	s_mov_b64 exec, s[74:75]
	v_mul_f32_e32 v196, v55, v55
	v_mul_f32_e32 v197, v57, v57
	v_mul_f32_e32 v198, v51, v51
	v_mul_f32_e32 v199, v53, v53
	v_fmac_f32_e32 v196, v54, v54
	v_fmac_f32_e32 v197, v56, v56
	v_fmac_f32_e32 v198, v50, v50
	v_fmac_f32_e32 v199, v52, v52
	v_pk_mul_f32 v[180:181], v[54:55], v[156:157]
	v_pk_mul_f32 v[182:183], v[56:57], v[158:159]
	v_pk_mul_f32 v[184:185], v[50:51], v[160:161]
	v_pk_mul_f32 v[186:187], v[52:53], v[162:163]
	v_add_f32_e32 v196, v196, v197
	v_add_f32_e32 v196, v198, v196
	v_add_f32_e32 v202, v199, v196
	v_cvt_pk_bf16_f32 v188, v180, v181
	v_cvt_pk_bf16_f32 v189, v182, v183
	v_cvt_pk_bf16_f32 v190, v184, v185
	v_cvt_pk_bf16_f32 v191, v186, v187
	v_mov_b32_e32 v203, v202
	global_store_dwordx4 v130, v[188:191], s[46:47] offset:256
	s_nop 1
	v_permlane16_swap_b32_e32 v202, v203
	v_add_f32_e32 v202, v202, v203
	v_mov_b32_e32 v203, v202
	s_nop 1
	v_permlane32_swap_b32_e32 v202, v203
	v_add_f32_e32 v202, v202, v203
	s_mov_b64 s[74:75], exec
	s_and_b64 exec, exec, s[68:69]
	global_atomic_add_f32 v132, v202, s[38:39]
	s_mov_b64 exec, s[74:75]
	v_mul_f32_e32 v192, v47, v47
	v_mul_f32_e32 v193, v49, v49
	v_mul_f32_e32 v194, v43, v43
	v_mul_f32_e32 v195, v45, v45
	v_fmac_f32_e32 v192, v46, v46
	v_fmac_f32_e32 v193, v48, v48
	v_fmac_f32_e32 v194, v42, v42
	v_fmac_f32_e32 v195, v44, v44
	v_pk_mul_f32 v[164:165], v[46:47], v[134:135]
	v_pk_mul_f32 v[166:167], v[48:49], v[136:137]
	v_pk_mul_f32 v[168:169], v[42:43], v[152:153]
	v_pk_mul_f32 v[170:171], v[44:45], v[154:155]
	v_add_f32_e32 v192, v192, v193
	v_add_f32_e32 v192, v194, v192
	v_add_f32_e32 v200, v195, v192
	v_cvt_pk_bf16_f32 v172, v164, v165
	v_cvt_pk_bf16_f32 v173, v166, v167
	v_cvt_pk_bf16_f32 v174, v168, v169
	v_cvt_pk_bf16_f32 v175, v170, v171
	v_mov_b32_e32 v201, v200
	s_add_u32 s46, s46, 0x2000
	s_addc_u32 s47, s47, 0
	s_add_u32 s38, s38, 0x40
	s_addc_u32 s39, s39, 0
	global_store_dwordx4 v130, v[172:175], s[46:47]
	s_nop 1
	v_permlane16_swap_b32_e32 v200, v201
	v_add_f32_e32 v200, v200, v201
	v_mov_b32_e32 v201, v200
	s_nop 1
	v_permlane32_swap_b32_e32 v200, v201
	v_add_f32_e32 v200, v200, v201
	s_mov_b64 s[74:75], exec
	s_and_b64 exec, exec, s[68:69]
	global_atomic_add_f32 v132, v200, s[38:39]
	s_mov_b64 exec, s[74:75]
	v_mul_f32_e32 v196, v39, v39
	v_mul_f32_e32 v197, v41, v41
	v_mul_f32_e32 v198, v35, v35
	v_mul_f32_e32 v199, v37, v37
	v_fmac_f32_e32 v196, v38, v38
	v_fmac_f32_e32 v197, v40, v40
	v_fmac_f32_e32 v198, v34, v34
	v_fmac_f32_e32 v199, v36, v36
	v_pk_mul_f32 v[180:181], v[38:39], v[156:157]
	v_pk_mul_f32 v[182:183], v[40:41], v[158:159]
	v_pk_mul_f32 v[184:185], v[34:35], v[160:161]
	v_pk_mul_f32 v[186:187], v[36:37], v[162:163]
	v_add_f32_e32 v196, v196, v197
	v_add_f32_e32 v196, v198, v196
	v_add_f32_e32 v202, v199, v196
	v_cvt_pk_bf16_f32 v188, v180, v181
	v_cvt_pk_bf16_f32 v189, v182, v183
	v_cvt_pk_bf16_f32 v190, v184, v185
	v_cvt_pk_bf16_f32 v191, v186, v187
	v_mov_b32_e32 v203, v202
	global_store_dwordx4 v130, v[188:191], s[46:47] offset:256
	s_nop 1
	v_permlane16_swap_b32_e32 v202, v203
	v_add_f32_e32 v202, v202, v203
	v_mov_b32_e32 v203, v202
	s_nop 1
	v_permlane32_swap_b32_e32 v202, v203
	v_add_f32_e32 v202, v202, v203
	s_mov_b64 s[74:75], exec
	s_and_b64 exec, exec, s[68:69]
	global_atomic_add_f32 v132, v202, s[38:39]
	s_mov_b64 exec, s[74:75]
	v_mul_f32_e32 v192, v31, v31
	v_mul_f32_e32 v193, v33, v33
	v_mul_f32_e32 v194, v27, v27
	v_mul_f32_e32 v195, v29, v29
	v_fmac_f32_e32 v192, v30, v30
	v_fmac_f32_e32 v193, v32, v32
	v_fmac_f32_e32 v194, v26, v26
	v_fmac_f32_e32 v195, v28, v28
	v_pk_mul_f32 v[164:165], v[30:31], v[134:135]
	v_pk_mul_f32 v[166:167], v[32:33], v[136:137]
	v_pk_mul_f32 v[168:169], v[26:27], v[152:153]
	v_pk_mul_f32 v[170:171], v[28:29], v[154:155]
	v_add_f32_e32 v192, v192, v193
	v_add_f32_e32 v192, v194, v192
	v_add_f32_e32 v200, v195, v192
	v_cvt_pk_bf16_f32 v172, v164, v165
	v_cvt_pk_bf16_f32 v173, v166, v167
	v_cvt_pk_bf16_f32 v174, v168, v169
	v_cvt_pk_bf16_f32 v175, v170, v171
	v_mov_b32_e32 v201, v200
	s_add_u32 s46, s46, 0x2000
	s_addc_u32 s47, s47, 0
	s_add_u32 s38, s38, 0x40
	s_addc_u32 s39, s39, 0
	global_store_dwordx4 v130, v[172:175], s[46:47]
	s_nop 1
	v_permlane16_swap_b32_e32 v200, v201
	v_add_f32_e32 v200, v200, v201
	v_mov_b32_e32 v201, v200
	s_nop 1
	v_permlane32_swap_b32_e32 v200, v201
	v_add_f32_e32 v200, v200, v201
	s_mov_b64 s[74:75], exec
	s_and_b64 exec, exec, s[68:69]
	global_atomic_add_f32 v132, v200, s[38:39]
	s_mov_b64 exec, s[74:75]
	v_mul_f32_e32 v196, v23, v23
	v_mul_f32_e32 v197, v25, v25
	v_mul_f32_e32 v198, v19, v19
	v_mul_f32_e32 v199, v21, v21
	v_fmac_f32_e32 v196, v22, v22
	v_fmac_f32_e32 v197, v24, v24
	v_fmac_f32_e32 v198, v18, v18
	v_fmac_f32_e32 v199, v20, v20
	v_pk_mul_f32 v[180:181], v[22:23], v[156:157]
	v_pk_mul_f32 v[182:183], v[24:25], v[158:159]
	v_pk_mul_f32 v[184:185], v[18:19], v[160:161]
	v_pk_mul_f32 v[186:187], v[20:21], v[162:163]
	v_add_f32_e32 v196, v196, v197
	v_add_f32_e32 v196, v198, v196
	v_add_f32_e32 v202, v199, v196
	v_cvt_pk_bf16_f32 v188, v180, v181
	v_cvt_pk_bf16_f32 v189, v182, v183
	v_cvt_pk_bf16_f32 v190, v184, v185
	v_cvt_pk_bf16_f32 v191, v186, v187
	v_mov_b32_e32 v203, v202
	global_store_dwordx4 v130, v[188:191], s[46:47] offset:256
	s_nop 1
	v_permlane16_swap_b32_e32 v202, v203
	v_add_f32_e32 v202, v202, v203
	v_mov_b32_e32 v203, v202
	s_nop 1
	v_permlane32_swap_b32_e32 v202, v203
	v_add_f32_e32 v202, v202, v203
	s_mov_b64 s[74:75], exec
	s_and_b64 exec, exec, s[68:69]
	global_atomic_add_f32 v132, v202, s[38:39]
	s_mov_b64 exec, s[74:75]
	v_mul_f32_e32 v192, v15, v15
	v_mul_f32_e32 v193, v17, v17
	v_mul_f32_e32 v194, v11, v11
	v_mul_f32_e32 v195, v13, v13
	v_fmac_f32_e32 v192, v14, v14
	v_fmac_f32_e32 v193, v16, v16
	v_fmac_f32_e32 v194, v10, v10
	v_fmac_f32_e32 v195, v12, v12
	v_pk_mul_f32 v[164:165], v[14:15], v[134:135]
	v_pk_mul_f32 v[166:167], v[16:17], v[136:137]
	v_pk_mul_f32 v[168:169], v[10:11], v[152:153]
	v_pk_mul_f32 v[170:171], v[12:13], v[154:155]
	v_add_f32_e32 v192, v192, v193
	v_add_f32_e32 v192, v194, v192
	v_add_f32_e32 v200, v195, v192
	v_cvt_pk_bf16_f32 v172, v164, v165
	v_cvt_pk_bf16_f32 v173, v166, v167
	v_cvt_pk_bf16_f32 v174, v168, v169
	v_cvt_pk_bf16_f32 v175, v170, v171
	v_mov_b32_e32 v201, v200
	s_add_u32 s46, s46, 0x2000
	s_addc_u32 s47, s47, 0
	s_add_u32 s38, s38, 0x40
	s_addc_u32 s39, s39, 0
	global_store_dwordx4 v130, v[172:175], s[46:47]
	s_nop 1
	v_permlane16_swap_b32_e32 v200, v201
	v_add_f32_e32 v200, v200, v201
	v_mov_b32_e32 v201, v200
	s_nop 1
	v_permlane32_swap_b32_e32 v200, v201
	v_add_f32_e32 v200, v200, v201
	s_mov_b64 s[74:75], exec
	s_and_b64 exec, exec, s[68:69]
	global_atomic_add_f32 v132, v200, s[38:39]
	s_mov_b64 exec, s[74:75]
	v_mul_f32_e32 v196, v7, v7
	v_mul_f32_e32 v197, v9, v9
	v_mul_f32_e32 v198, v3, v3
	v_mul_f32_e32 v199, v5, v5
	v_fmac_f32_e32 v196, v6, v6
	v_fmac_f32_e32 v197, v8, v8
	v_fmac_f32_e32 v198, v2, v2
	v_fmac_f32_e32 v199, v4, v4
	v_pk_mul_f32 v[180:181], v[6:7], v[156:157]
	v_pk_mul_f32 v[182:183], v[8:9], v[158:159]
	v_pk_mul_f32 v[184:185], v[2:3], v[160:161]
	v_pk_mul_f32 v[186:187], v[4:5], v[162:163]
	v_add_f32_e32 v196, v196, v197
	v_add_f32_e32 v196, v198, v196
	v_add_f32_e32 v202, v199, v196
	v_cvt_pk_bf16_f32 v188, v180, v181
	v_cvt_pk_bf16_f32 v189, v182, v183
	v_cvt_pk_bf16_f32 v190, v184, v185
	v_cvt_pk_bf16_f32 v191, v186, v187
	v_mov_b32_e32 v203, v202
	global_store_dwordx4 v130, v[188:191], s[46:47] offset:256
	s_nop 1
	v_permlane16_swap_b32_e32 v202, v203
	v_add_f32_e32 v202, v202, v203
	v_mov_b32_e32 v203, v202
	s_nop 1
	v_permlane32_swap_b32_e32 v202, v203
	v_add_f32_e32 v202, v202, v203
	s_mov_b64 s[74:75], exec
	s_and_b64 exec, exec, s[68:69]
	global_atomic_add_f32 v132, v202, s[38:39]
	s_mov_b64 exec, s[74:75]
	s_branch .LBB0_1251
.Lepi_w1:
	s_lshl_b32 s9, s9, 8
	s_add_i32 s9, s9, s60
	s_lshl_b32 s78, s8, 8
	s_or_b32 s78, s78, s26
	s_mov_b32 s8, s9
	s_mul_i32 s9, s9, 0x2000
	s_mul_i32 s41, s78, 2
	s_add_i32 s9, s9, s41
	s_add_u32 s46, s36, s9
	s_addc_u32 s47, s37, 0
	s_add_u32 s46, s46, 0x7600000
	s_addc_u32 s47, s47, 0
	v_lshlrev_b32_e32 v130, 13, v1
	v_lshl_add_u32 v130, v176, 1, v130
	v_max_f32_e32 v152, 0, v126
	v_max_f32_e32 v153, 0, v127
	v_max_f32_e32 v154, 0, v128
	v_max_f32_e32 v155, 0, v129
	v_max_f32_e32 v156, 0, v122
	v_max_f32_e32 v157, 0, v123
	v_max_f32_e32 v158, 0, v124
	v_max_f32_e32 v159, 0, v125
	v_pk_mul_f32 v[152:153], v[152:153], v[152:153]
	v_pk_mul_f32 v[154:155], v[154:155], v[154:155]
	v_pk_mul_f32 v[156:157], v[156:157], v[156:157]
	v_pk_mul_f32 v[158:159], v[158:159], v[158:159]
	v_cvt_pk_bf16_f32 v132, v152, v153
	v_cvt_pk_bf16_f32 v133, v154, v155
	v_cvt_pk_bf16_f32 v134, v156, v157
	v_cvt_pk_bf16_f32 v135, v158, v159
	global_store_dwordx4 v130, v[132:135], s[46:47]
	v_max_f32_e32 v160, 0, v118
	v_max_f32_e32 v161, 0, v119
	v_max_f32_e32 v162, 0, v120
	v_max_f32_e32 v163, 0, v121
	v_max_f32_e32 v164, 0, v114
	v_max_f32_e32 v165, 0, v115
	v_max_f32_e32 v166, 0, v116
	v_max_f32_e32 v167, 0, v117
	v_pk_mul_f32 v[160:161], v[160:161], v[160:161]
	v_pk_mul_f32 v[162:163], v[162:163], v[162:163]
	v_pk_mul_f32 v[164:165], v[164:165], v[164:165]
	v_pk_mul_f32 v[166:167], v[166:167], v[166:167]
	v_cvt_pk_bf16_f32 v168, v160, v161
	v_cvt_pk_bf16_f32 v169, v162, v163
	v_cvt_pk_bf16_f32 v170, v164, v165
	v_cvt_pk_bf16_f32 v171, v166, v167
	global_store_dwordx4 v130, v[168:171], s[46:47] offset:256
	v_max_f32_e32 v152, 0, v110
	v_max_f32_e32 v153, 0, v111
	v_max_f32_e32 v154, 0, v112
	v_max_f32_e32 v155, 0, v113
	v_max_f32_e32 v156, 0, v106
	v_max_f32_e32 v157, 0, v107
	v_max_f32_e32 v158, 0, v108
	v_max_f32_e32 v159, 0, v109
	v_pk_mul_f32 v[152:153], v[152:153], v[152:153]
	v_pk_mul_f32 v[154:155], v[154:155], v[154:155]
	v_pk_mul_f32 v[156:157], v[156:157], v[156:157]
	v_pk_mul_f32 v[158:159], v[158:159], v[158:159]
	v_cvt_pk_bf16_f32 v132, v152, v153
	v_cvt_pk_bf16_f32 v133, v154, v155
	v_cvt_pk_bf16_f32 v134, v156, v157
	v_cvt_pk_bf16_f32 v135, v158, v159
	s_add_u32 s46, s46, 0x20000
	s_addc_u32 s47, s47, 0
	global_store_dwordx4 v130, v[132:135], s[46:47]
	v_max_f32_e32 v160, 0, v102
	v_max_f32_e32 v161, 0, v103
	v_max_f32_e32 v162, 0, v104
	v_max_f32_e32 v163, 0, v105
	v_max_f32_e32 v164, 0, v98
	v_max_f32_e32 v165, 0, v99
	v_max_f32_e32 v166, 0, v100
	v_max_f32_e32 v167, 0, v101
	v_pk_mul_f32 v[160:161], v[160:161], v[160:161]
	v_pk_mul_f32 v[162:163], v[162:163], v[162:163]
	v_pk_mul_f32 v[164:165], v[164:165], v[164:165]
	v_pk_mul_f32 v[166:167], v[166:167], v[166:167]
	v_cvt_pk_bf16_f32 v168, v160, v161
	v_cvt_pk_bf16_f32 v169, v162, v163
	v_cvt_pk_bf16_f32 v170, v164, v165
	v_cvt_pk_bf16_f32 v171, v166, v167
	global_store_dwordx4 v130, v[168:171], s[46:47] offset:256
	v_max_f32_e32 v152, 0, v94
	v_max_f32_e32 v153, 0, v95
	v_max_f32_e32 v154, 0, v96
	v_max_f32_e32 v155, 0, v97
	v_max_f32_e32 v156, 0, v90
	v_max_f32_e32 v157, 0, v91
	v_max_f32_e32 v158, 0, v92
	v_max_f32_e32 v159, 0, v93
	v_pk_mul_f32 v[152:153], v[152:153], v[152:153]
	v_pk_mul_f32 v[154:155], v[154:155], v[154:155]
	v_pk_mul_f32 v[156:157], v[156:157], v[156:157]
	v_pk_mul_f32 v[158:159], v[158:159], v[158:159]
	v_cvt_pk_bf16_f32 v132, v152, v153
	v_cvt_pk_bf16_f32 v133, v154, v155
	v_cvt_pk_bf16_f32 v134, v156, v157
	v_cvt_pk_bf16_f32 v135, v158, v159
	s_add_u32 s46, s46, 0x20000
	s_addc_u32 s47, s47, 0
	global_store_dwordx4 v130, v[132:135], s[46:47]
	v_max_f32_e32 v160, 0, v86
	v_max_f32_e32 v161, 0, v87
	v_max_f32_e32 v162, 0, v88
	v_max_f32_e32 v163, 0, v89
	v_max_f32_e32 v164, 0, v82
	v_max_f32_e32 v165, 0, v83
	v_max_f32_e32 v166, 0, v84
	v_max_f32_e32 v167, 0, v85
	v_pk_mul_f32 v[160:161], v[160:161], v[160:161]
	v_pk_mul_f32 v[162:163], v[162:163], v[162:163]
	v_pk_mul_f32 v[164:165], v[164:165], v[164:165]
	v_pk_mul_f32 v[166:167], v[166:167], v[166:167]
	v_cvt_pk_bf16_f32 v168, v160, v161
	v_cvt_pk_bf16_f32 v169, v162, v163
	v_cvt_pk_bf16_f32 v170, v164, v165
	v_cvt_pk_bf16_f32 v171, v166, v167
	global_store_dwordx4 v130, v[168:171], s[46:47] offset:256
	v_max_f32_e32 v152, 0, v78
	v_max_f32_e32 v153, 0, v79
	v_max_f32_e32 v154, 0, v80
	v_max_f32_e32 v155, 0, v81
	v_max_f32_e32 v156, 0, v74
	v_max_f32_e32 v157, 0, v75
	v_max_f32_e32 v158, 0, v76
	v_max_f32_e32 v159, 0, v77
	v_pk_mul_f32 v[152:153], v[152:153], v[152:153]
	v_pk_mul_f32 v[154:155], v[154:155], v[154:155]
	v_pk_mul_f32 v[156:157], v[156:157], v[156:157]
	v_pk_mul_f32 v[158:159], v[158:159], v[158:159]
	v_cvt_pk_bf16_f32 v132, v152, v153
	v_cvt_pk_bf16_f32 v133, v154, v155
	v_cvt_pk_bf16_f32 v134, v156, v157
	v_cvt_pk_bf16_f32 v135, v158, v159
	s_add_u32 s46, s46, 0x20000
	s_addc_u32 s47, s47, 0
	global_store_dwordx4 v130, v[132:135], s[46:47]
	v_max_f32_e32 v160, 0, v70
	v_max_f32_e32 v161, 0, v71
	v_max_f32_e32 v162, 0, v72
	v_max_f32_e32 v163, 0, v73
	v_max_f32_e32 v164, 0, v66
	v_max_f32_e32 v165, 0, v67
	v_max_f32_e32 v166, 0, v68
	v_max_f32_e32 v167, 0, v69
	v_pk_mul_f32 v[160:161], v[160:161], v[160:161]
	v_pk_mul_f32 v[162:163], v[162:163], v[162:163]
	v_pk_mul_f32 v[164:165], v[164:165], v[164:165]
	v_pk_mul_f32 v[166:167], v[166:167], v[166:167]
	v_cvt_pk_bf16_f32 v168, v160, v161
	v_cvt_pk_bf16_f32 v169, v162, v163
	v_cvt_pk_bf16_f32 v170, v164, v165
	v_cvt_pk_bf16_f32 v171, v166, v167
	global_store_dwordx4 v130, v[168:171], s[46:47] offset:256
	v_max_f32_e32 v152, 0, v62
	v_max_f32_e32 v153, 0, v63
	v_max_f32_e32 v154, 0, v64
	v_max_f32_e32 v155, 0, v65
	v_max_f32_e32 v156, 0, v58
	v_max_f32_e32 v157, 0, v59
	v_max_f32_e32 v158, 0, v60
	v_max_f32_e32 v159, 0, v61
	v_pk_mul_f32 v[152:153], v[152:153], v[152:153]
	v_pk_mul_f32 v[154:155], v[154:155], v[154:155]
	v_pk_mul_f32 v[156:157], v[156:157], v[156:157]
	v_pk_mul_f32 v[158:159], v[158:159], v[158:159]
	v_cvt_pk_bf16_f32 v132, v152, v153
	v_cvt_pk_bf16_f32 v133, v154, v155
	v_cvt_pk_bf16_f32 v134, v156, v157
	v_cvt_pk_bf16_f32 v135, v158, v159
	s_add_u32 s46, s46, 0xa0000
	s_addc_u32 s47, s47, 0
	global_store_dwordx4 v130, v[132:135], s[46:47]
	v_max_f32_e32 v160, 0, v54
	v_max_f32_e32 v161, 0, v55
	v_max_f32_e32 v162, 0, v56
	v_max_f32_e32 v163, 0, v57
	v_max_f32_e32 v164, 0, v50
	v_max_f32_e32 v165, 0, v51
	v_max_f32_e32 v166, 0, v52
	v_max_f32_e32 v167, 0, v53
	v_pk_mul_f32 v[160:161], v[160:161], v[160:161]
	v_pk_mul_f32 v[162:163], v[162:163], v[162:163]
	v_pk_mul_f32 v[164:165], v[164:165], v[164:165]
	v_pk_mul_f32 v[166:167], v[166:167], v[166:167]
	v_cvt_pk_bf16_f32 v168, v160, v161
	v_cvt_pk_bf16_f32 v169, v162, v163
	v_cvt_pk_bf16_f32 v170, v164, v165
	v_cvt_pk_bf16_f32 v171, v166, v167
	global_store_dwordx4 v130, v[168:171], s[46:47] offset:256
	v_max_f32_e32 v152, 0, v46
	v_max_f32_e32 v153, 0, v47
	v_max_f32_e32 v154, 0, v48
	v_max_f32_e32 v155, 0, v49
	v_max_f32_e32 v156, 0, v42
	v_max_f32_e32 v157, 0, v43
	v_max_f32_e32 v158, 0, v44
	v_max_f32_e32 v159, 0, v45
	v_pk_mul_f32 v[152:153], v[152:153], v[152:153]
	v_pk_mul_f32 v[154:155], v[154:155], v[154:155]
	v_pk_mul_f32 v[156:157], v[156:157], v[156:157]
	v_pk_mul_f32 v[158:159], v[158:159], v[158:159]
	v_cvt_pk_bf16_f32 v132, v152, v153
	v_cvt_pk_bf16_f32 v133, v154, v155
	v_cvt_pk_bf16_f32 v134, v156, v157
	v_cvt_pk_bf16_f32 v135, v158, v159
	s_add_u32 s46, s46, 0x20000
	s_addc_u32 s47, s47, 0
	global_store_dwordx4 v130, v[132:135], s[46:47]
	v_max_f32_e32 v160, 0, v38
	v_max_f32_e32 v161, 0, v39
	v_max_f32_e32 v162, 0, v40
	v_max_f32_e32 v163, 0, v41
	v_max_f32_e32 v164, 0, v34
	v_max_f32_e32 v165, 0, v35
	v_max_f32_e32 v166, 0, v36
	v_max_f32_e32 v167, 0, v37
	v_pk_mul_f32 v[160:161], v[160:161], v[160:161]
	v_pk_mul_f32 v[162:163], v[162:163], v[162:163]
	v_pk_mul_f32 v[164:165], v[164:165], v[164:165]
	v_pk_mul_f32 v[166:167], v[166:167], v[166:167]
	v_cvt_pk_bf16_f32 v168, v160, v161
	v_cvt_pk_bf16_f32 v169, v162, v163
	v_cvt_pk_bf16_f32 v170, v164, v165
	v_cvt_pk_bf16_f32 v171, v166, v167
	global_store_dwordx4 v130, v[168:171], s[46:47] offset:256
	v_max_f32_e32 v152, 0, v30
	v_max_f32_e32 v153, 0, v31
	v_max_f32_e32 v154, 0, v32
	v_max_f32_e32 v155, 0, v33
	v_max_f32_e32 v156, 0, v26
	v_max_f32_e32 v157, 0, v27
	v_max_f32_e32 v158, 0, v28
	v_max_f32_e32 v159, 0, v29
	v_pk_mul_f32 v[152:153], v[152:153], v[152:153]
	v_pk_mul_f32 v[154:155], v[154:155], v[154:155]
	v_pk_mul_f32 v[156:157], v[156:157], v[156:157]
	v_pk_mul_f32 v[158:159], v[158:159], v[158:159]
	v_cvt_pk_bf16_f32 v132, v152, v153
	v_cvt_pk_bf16_f32 v133, v154, v155
	v_cvt_pk_bf16_f32 v134, v156, v157
	v_cvt_pk_bf16_f32 v135, v158, v159
	s_add_u32 s46, s46, 0x20000
	s_addc_u32 s47, s47, 0
	global_store_dwordx4 v130, v[132:135], s[46:47]
	v_max_f32_e32 v160, 0, v22
	v_max_f32_e32 v161, 0, v23
	v_max_f32_e32 v162, 0, v24
	v_max_f32_e32 v163, 0, v25
	v_max_f32_e32 v164, 0, v18
	v_max_f32_e32 v165, 0, v19
	v_max_f32_e32 v166, 0, v20
	v_max_f32_e32 v167, 0, v21
	v_pk_mul_f32 v[160:161], v[160:161], v[160:161]
	v_pk_mul_f32 v[162:163], v[162:163], v[162:163]
	v_pk_mul_f32 v[164:165], v[164:165], v[164:165]
	v_pk_mul_f32 v[166:167], v[166:167], v[166:167]
	v_cvt_pk_bf16_f32 v168, v160, v161
	v_cvt_pk_bf16_f32 v169, v162, v163
	v_cvt_pk_bf16_f32 v170, v164, v165
	v_cvt_pk_bf16_f32 v171, v166, v167
	global_store_dwordx4 v130, v[168:171], s[46:47] offset:256
	v_max_f32_e32 v152, 0, v14
	v_max_f32_e32 v153, 0, v15
	v_max_f32_e32 v154, 0, v16
	v_max_f32_e32 v155, 0, v17
	v_max_f32_e32 v156, 0, v10
	v_max_f32_e32 v157, 0, v11
	v_max_f32_e32 v158, 0, v12
	v_max_f32_e32 v159, 0, v13
	v_pk_mul_f32 v[152:153], v[152:153], v[152:153]
	v_pk_mul_f32 v[154:155], v[154:155], v[154:155]
	v_pk_mul_f32 v[156:157], v[156:157], v[156:157]
	v_pk_mul_f32 v[158:159], v[158:159], v[158:159]
	v_cvt_pk_bf16_f32 v132, v152, v153
	v_cvt_pk_bf16_f32 v133, v154, v155
	v_cvt_pk_bf16_f32 v134, v156, v157
	v_cvt_pk_bf16_f32 v135, v158, v159
	s_add_u32 s46, s46, 0x20000
	s_addc_u32 s47, s47, 0
	global_store_dwordx4 v130, v[132:135], s[46:47]
	v_max_f32_e32 v160, 0, v6
	v_max_f32_e32 v161, 0, v7
	v_max_f32_e32 v162, 0, v8
	v_max_f32_e32 v163, 0, v9
	v_max_f32_e32 v164, 0, v2
	v_max_f32_e32 v165, 0, v3
	v_max_f32_e32 v166, 0, v4
	v_max_f32_e32 v167, 0, v5
	v_pk_mul_f32 v[160:161], v[160:161], v[160:161]
	v_pk_mul_f32 v[162:163], v[162:163], v[162:163]
	v_pk_mul_f32 v[164:165], v[164:165], v[164:165]
	v_pk_mul_f32 v[166:167], v[166:167], v[166:167]
	v_cvt_pk_bf16_f32 v168, v160, v161
	v_cvt_pk_bf16_f32 v169, v162, v163
	v_cvt_pk_bf16_f32 v170, v164, v165
	v_cvt_pk_bf16_f32 v171, v166, v167
	global_store_dwordx4 v130, v[168:171], s[46:47] offset:256
	s_branch .LBB0_1251
.Lepi_projt:
	s_lshl_b32 s9, s9, 8
	s_add_i32 s9, s9, s60
	s_lshl_b32 s78, s8, 8
	s_or_b32 s78, s78, s26
	s_cmp_lt_u32 s9, 0x200
	s_cselect_b32 s41, 0, 0x200
	s_cselect_b32 s48, 16, 17
	s_mov_b32 s68, 0x19600000
	s_cselect_b32 s68, s68, 0xf600000
	s_sub_i32 s9, s9, s41
	s_lshr_b32 s8, s78, 6
	s_lshl_b32 s8, s8, s48
	s_lshl_b32 s9, s9, 7
	s_add_i32 s8, s8, s9
	s_and_b32 s9, s78, 63
	s_lshl_b32 s9, s9, 1
	s_add_i32 s8, s8, s9
	s_add_u32 s46, s36, s8
	s_addc_u32 s47, s37, 0
	s_add_u32 s46, s46, s68
	s_addc_u32 s47, s47, 0
	s_lshl_b32 s41, 2, s48
	v_lshlrev_b32_e32 v130, 7, v1
	v_lshl_add_u32 v130, v176, 1, v130
	v_add_u32_e32 v131, s41, v130
	v_cvt_pk_bf16_f32 v132, v126, v127
	v_cvt_pk_bf16_f32 v133, v128, v129
	v_cvt_pk_bf16_f32 v134, v122, v123
	v_cvt_pk_bf16_f32 v135, v124, v125
	global_store_dwordx4 v130, v[132:135], s[46:47]
	v_cvt_pk_bf16_f32 v152, v118, v119
	v_cvt_pk_bf16_f32 v153, v120, v121
	v_cvt_pk_bf16_f32 v154, v114, v115
	v_cvt_pk_bf16_f32 v155, v116, v117
	global_store_dwordx4 v131, v[152:155], s[46:47]
	v_cvt_pk_bf16_f32 v132, v110, v111
	v_cvt_pk_bf16_f32 v133, v112, v113
	v_cvt_pk_bf16_f32 v134, v106, v107
	v_cvt_pk_bf16_f32 v135, v108, v109
	s_add_u32 s46, s46, 0x800
	s_addc_u32 s47, s47, 0
	global_store_dwordx4 v130, v[132:135], s[46:47]
	v_cvt_pk_bf16_f32 v152, v102, v103
	v_cvt_pk_bf16_f32 v153, v104, v105
	v_cvt_pk_bf16_f32 v154, v98, v99
	v_cvt_pk_bf16_f32 v155, v100, v101
	global_store_dwordx4 v131, v[152:155], s[46:47]
	v_cvt_pk_bf16_f32 v132, v94, v95
	v_cvt_pk_bf16_f32 v133, v96, v97
	v_cvt_pk_bf16_f32 v134, v90, v91
	v_cvt_pk_bf16_f32 v135, v92, v93
	s_add_u32 s46, s46, 0x800
	s_addc_u32 s47, s47, 0
	global_store_dwordx4 v130, v[132:135], s[46:47]
	v_cvt_pk_bf16_f32 v152, v86, v87
	v_cvt_pk_bf16_f32 v153, v88, v89
	v_cvt_pk_bf16_f32 v154, v82, v83
	v_cvt_pk_bf16_f32 v155, v84, v85
	global_store_dwordx4 v131, v[152:155], s[46:47]
	v_cvt_pk_bf16_f32 v132, v78, v79
	v_cvt_pk_bf16_f32 v133, v80, v81
	v_cvt_pk_bf16_f32 v134, v74, v75
	v_cvt_pk_bf16_f32 v135, v76, v77
	s_add_u32 s46, s46, 0x800
	s_addc_u32 s47, s47, 0
	global_store_dwordx4 v130, v[132:135], s[46:47]
	v_cvt_pk_bf16_f32 v152, v70, v71
	v_cvt_pk_bf16_f32 v153, v72, v73
	v_cvt_pk_bf16_f32 v154, v66, v67
	v_cvt_pk_bf16_f32 v155, v68, v69
	global_store_dwordx4 v131, v[152:155], s[46:47]
	v_cvt_pk_bf16_f32 v132, v62, v63
	v_cvt_pk_bf16_f32 v133, v64, v65
	v_cvt_pk_bf16_f32 v134, v58, v59
	v_cvt_pk_bf16_f32 v135, v60, v61
	s_add_u32 s46, s46, 0x2800
	s_addc_u32 s47, s47, 0
	global_store_dwordx4 v130, v[132:135], s[46:47]
	v_cvt_pk_bf16_f32 v152, v54, v55
	v_cvt_pk_bf16_f32 v153, v56, v57
	v_cvt_pk_bf16_f32 v154, v50, v51
	v_cvt_pk_bf16_f32 v155, v52, v53
	global_store_dwordx4 v131, v[152:155], s[46:47]
	v_cvt_pk_bf16_f32 v132, v46, v47
	v_cvt_pk_bf16_f32 v133, v48, v49
	v_cvt_pk_bf16_f32 v134, v42, v43
	v_cvt_pk_bf16_f32 v135, v44, v45
	s_add_u32 s46, s46, 0x800
	s_addc_u32 s47, s47, 0
	global_store_dwordx4 v130, v[132:135], s[46:47]
	v_cvt_pk_bf16_f32 v152, v38, v39
	v_cvt_pk_bf16_f32 v153, v40, v41
	v_cvt_pk_bf16_f32 v154, v34, v35
	v_cvt_pk_bf16_f32 v155, v36, v37
	global_store_dwordx4 v131, v[152:155], s[46:47]
	v_cvt_pk_bf16_f32 v132, v30, v31
	v_cvt_pk_bf16_f32 v133, v32, v33
	v_cvt_pk_bf16_f32 v134, v26, v27
	v_cvt_pk_bf16_f32 v135, v28, v29
	s_add_u32 s46, s46, 0x800
	s_addc_u32 s47, s47, 0
	global_store_dwordx4 v130, v[132:135], s[46:47]
	v_cvt_pk_bf16_f32 v152, v22, v23
	v_cvt_pk_bf16_f32 v153, v24, v25
	v_cvt_pk_bf16_f32 v154, v18, v19
	v_cvt_pk_bf16_f32 v155, v20, v21
	global_store_dwordx4 v131, v[152:155], s[46:47]
	v_cvt_pk_bf16_f32 v132, v14, v15
	v_cvt_pk_bf16_f32 v133, v16, v17
	v_cvt_pk_bf16_f32 v134, v10, v11
	v_cvt_pk_bf16_f32 v135, v12, v13
	s_add_u32 s46, s46, 0x800
	s_addc_u32 s47, s47, 0
	global_store_dwordx4 v130, v[132:135], s[46:47]
	v_cvt_pk_bf16_f32 v152, v6, v7
	v_cvt_pk_bf16_f32 v153, v8, v9
	v_cvt_pk_bf16_f32 v154, v2, v3
	v_cvt_pk_bf16_f32 v155, v4, v5
	global_store_dwordx4 v131, v[152:155], s[46:47]
	s_branch .LBB0_1251
